# v51 + scheduler gsz division replaced by shift/and (gsz is always 8) + first K-tile fragment ds_reads hoisted above the next-unit scalar block in all 6 GEMM unit headers
# speedup vs baseline: 1.0085x; 1.0085x over previous
.LBB0_167:
	v_cmp_gt_i64_e32 vcc, s[18:19], v[158:159]
	s_mov_b64 s[20:21], -1
	s_cbranch_vccnz .LBB0_166
	s_ashr_i32 s20, s18, 31
	s_lshr_b32 s20, s20, 29
	s_add_i32 s20, s18, s20
	s_ashr_i32 s21, s20, 3
	s_and_b32 s20, s20, -8
	s_sub_i32 s20, s18, s20
	s_cmp_lt_i32 s20, 0
	s_cselect_b32 s46, s36, 0x160
	s_mul_i32 s20, s20, s46
	s_add_i32 s20, s20, s21
	s_mul_hi_i32 s21, s20, 0x2e8ba2e9
	s_lshr_b32 s46, s21, 31
	s_ashr_i32 s21, s21, 5
	s_add_i32 s21, s21, s46
	s_lshl_b32 s46, s21, 3
	s_sub_i32 s48, 0x80, s46
	s_min_i32 s48, s48, 8
	s_mulk_i32 s21, 0xb0
	s_sub_i32 s20, s20, s21
	s_and_b32 s20, s20, 7
	s_add_i32 s46, s46, s20
	s_cmp_eq_u32 s46, s47
	s_cbranch_scc1 .LBB0_165
	v_lshl_add_u32 v2, s46, 8, v0
	s_waitcnt lgkmcnt(0)
	v_ashrrev_i32_e32 v3, 31, v2
	v_lshlrev_b64 v[2:3], 6, v[2:3]
	v_lshl_add_u64 v[2:3], s[28:29], 0, v[2:3]
	v_lshl_add_u64 v[6:7], v[2:3], 0, v[152:153]
	global_load_dwordx4 v[2:5], v[6:7], off
	s_nop 0
	global_load_dwordx4 v[6:9], v[6:7], off offset:16
	v_cmp_lt_i32_e32 vcc, v206, v205
	s_waitcnt vmcnt(0)
	v_pk_add_f32 v[4:5], v[4:5], v[8:9]
	v_pk_add_f32 v[2:3], v[2:3], v[6:7]
	s_nop 0
	v_add_f32_e32 v2, v2, v3
	v_add_f32_e32 v3, v4, v5
	v_add_f32_e32 v2, v2, v3
	v_cndmask_b32_e32 v3, v204, v206, vcc
	v_lshlrev_b32_e32 v3, 2, v3
	ds_bpermute_b32 v3, v3, v2
	s_and_saveexec_b64 s[20:21], s[44:45]
	s_cbranch_execz .LBB0_164
	s_waitcnt lgkmcnt(0)
	v_add_f32_e32 v2, v2, v3
	v_fmamk_f32 v2, v2, 0x3a800000, v202
	s_mov_b32 s47, 0x800000
	v_cmp_gt_f32_e32 vcc, s47, v2
	v_mul_f32_e32 v3, 0x4b800000, v2
	s_lshl_b32 s47, s46, 7
	v_cndmask_b32_e32 v2, v2, v3, vcc
	v_rsq_f32_e32 v2, v2
	s_and_b32 s47, s47, 0xc00
	v_mul_f32_e32 v3, 0x45800000, v2
	v_cndmask_b32_e32 v2, v2, v3, vcc
	v_add_u32_e32 v3, s47, v1
	ds_write_b32 v3, v2
	s_branch .LBB0_164

.LBB0_177:
	s_add_i32 s86, 0, 0x10000
	v_add_u32_e32 v142, s86, v145
	s_add_i32 s92, 0, 0x14000
	ds_read_b128 v[138:141], v142
	ds_read_b128 v[172:175], v142 offset:1024
	ds_read_b128 v[176:179], v142 offset:2048
	ds_read_b128 v[180:183], v142 offset:3072
	v_add_u32_e32 v142, s92, v145
	ds_read_b128 v[184:187], v142
	ds_read_b128 v[188:191], v142 offset:1024
	ds_read_b128 v[192:195], v142 offset:2048
	ds_read_b128 v[196:199], v142 offset:3072
	ds_read_b128 v[210:213], v148
	ds_read_b128 v[214:217], v148 offset:1024
	ds_read_b128 v[218:221], v148 offset:2048
	ds_read_b128 v[224:227], v148 offset:3072
	ds_read_b128 v[228:231], v148 offset:4096
	ds_read_b128 v[232:235], v148 offset:5120
	ds_read_b128 v[236:239], v148 offset:6144
	ds_read_b128 v[240:243], v148 offset:7168
	s_add_i32 s79, s79, 1
	s_mul_i32 s21, s79, s33
	s_mul_hi_u32 s44, s79, s94
	s_add_i32 s44, s44, s21
	s_mul_i32 s21, s79, s94
	s_add_u32 s48, s21, s2
	s_addc_u32 s49, s44, s3
	v_cmp_gt_i64_e32 vcc, s[48:49], v[158:159]
	v_cmp_lt_i64_e64 s[44:45], s[48:49], v[160:161]
	s_cbranch_vccnz .LBB0_179
	s_ashr_i32 s20, s48, 31
	s_lshr_b32 s20, s20, 29
	s_add_i32 s20, s48, s20
	s_ashr_i32 s21, s20, 3
	s_and_b32 s20, s20, -8
	s_sub_i32 s20, s48, s20
	s_cmp_lt_i32 s20, 0
	s_cselect_b32 s46, s36, 0x160
	s_mul_i32 s20, s20, s46
	s_add_i32 s20, s20, s21
	s_mul_hi_i32 s21, s20, 0x2e8ba2e9
	s_lshr_b32 s46, s21, 31
	s_ashr_i32 s21, s21, 5
	s_add_i32 s21, s21, s46
	s_lshl_b32 s46, s21, 3
	s_sub_i32 s47, 0x80, s46
	s_min_i32 s47, s47, 8
	s_mulk_i32 s21, 0xb0
	s_sub_i32 s21, s20, s21
	s_lshr_b32 s20, s21, 3
	s_and_b32 s21, s21, 7
	s_add_i32 s46, s46, s21
.LBB0_179:
	s_ashr_i32 s47, s46, 31
	s_lshl_b64 s[48:49], s[46:47], 19
	s_add_u32 s48, s26, s48
	s_addc_u32 s49, s27, s49
	s_and_b64 s[50:51], s[44:45], exec
	s_cselect_b32 s47, s49, s63
	s_cselect_b32 s82, s48, s62
	s_ashr_i32 s21, s20, 31
	s_lshl_b64 s[50:51], s[20:21], 19
	s_add_u32 s50, s59, s50
	s_addc_u32 s51, s66, s51
	s_and_b64 s[84:85], s[44:45], exec
	s_cselect_b32 s21, s51, s61
	s_cselect_b32 s83, s50, s60
	s_add_u32 s89, s60, 0x100
	s_addc_u32 s84, s61, 0
	s_add_u32 s60, s62, 0x40080
	s_addc_u32 s61, s63, 0
	s_mov_b32 s85, -2
	s_add_u32 s62, s60, 0xfffc0080
	s_addc_u32 s63, s61, -1
	s_cmp_eq_u32 s85, 12
	s_cselect_b32 vcc_hi, s47, s63
	s_cselect_b32 vcc_lo, s82, s62
	s_cselect_b32 s63, s21, s84
	s_cselect_b32 s62, s83, s89
	v_lshl_add_u64 v[142:143], s[60:61], 0, v[136:137]
	s_add_i32 m0, s68, 0xc000
	global_load_lds_dwordx4 v[142:143], off
	v_lshl_add_u64 v[142:143], s[60:61], 0, v[134:135]
	s_add_i32 m0, s68, 0xe000
	s_nop 0
	global_load_lds_dwordx4 v[142:143], off
	s_waitcnt vmcnt(8)
	s_waitcnt lgkmcnt(0)
	s_barrier
	s_setprio 1
	s_waitcnt lgkmcnt(0)
	v_mfma_f32_16x16x32_bf16 v[124:127], v[138:141], v[210:213], 0
	v_mfma_f32_16x16x32_bf16 v[116:119], v[176:179], v[210:213], 0
	v_mfma_f32_16x16x32_bf16 v[108:111], v[138:141], v[218:221], 0
	v_mfma_f32_16x16x32_bf16 v[100:103], v[176:179], v[218:221], 0
	v_mfma_f32_16x16x32_bf16 v[92:95], v[138:141], v[228:231], 0
	v_mfma_f32_16x16x32_bf16 v[84:87], v[176:179], v[228:231], 0
	v_mfma_f32_16x16x32_bf16 v[76:79], v[138:141], v[236:239], 0
	v_mfma_f32_16x16x32_bf16 v[68:71], v[176:179], v[236:239], 0
	v_mfma_f32_16x16x32_bf16 v[124:127], v[172:175], v[214:217], v[124:127]
	v_mfma_f32_16x16x32_bf16 v[116:119], v[180:183], v[214:217], v[116:119]
	v_mfma_f32_16x16x32_bf16 v[108:111], v[172:175], v[224:227], v[108:111]
	v_mfma_f32_16x16x32_bf16 v[100:103], v[180:183], v[224:227], v[100:103]
	v_mfma_f32_16x16x32_bf16 v[92:95], v[172:175], v[232:235], v[92:95]
	v_mfma_f32_16x16x32_bf16 v[84:87], v[180:183], v[232:235], v[84:87]
	v_mfma_f32_16x16x32_bf16 v[76:79], v[172:175], v[240:243], v[76:79]
	v_mfma_f32_16x16x32_bf16 v[68:71], v[180:183], v[240:243], v[68:71]
	s_setprio 0
	s_setprio 1
	v_mfma_f32_16x16x32_bf16 v[120:123], v[184:187], v[210:213], 0
	v_mfma_f32_16x16x32_bf16 v[112:115], v[192:195], v[210:213], 0
	v_mfma_f32_16x16x32_bf16 v[104:107], v[184:187], v[218:221], 0
	v_mfma_f32_16x16x32_bf16 v[96:99], v[192:195], v[218:221], 0
	v_mfma_f32_16x16x32_bf16 v[88:91], v[184:187], v[228:231], 0
	v_mfma_f32_16x16x32_bf16 v[80:83], v[192:195], v[228:231], 0
	v_mfma_f32_16x16x32_bf16 v[72:75], v[184:187], v[236:239], 0
	v_mfma_f32_16x16x32_bf16 v[64:67], v[192:195], v[236:239], 0
	v_mfma_f32_16x16x32_bf16 v[120:123], v[188:191], v[214:217], v[120:123]
	v_mfma_f32_16x16x32_bf16 v[112:115], v[196:199], v[214:217], v[112:115]
	v_mfma_f32_16x16x32_bf16 v[104:107], v[188:191], v[224:227], v[104:107]
	v_mfma_f32_16x16x32_bf16 v[96:99], v[196:199], v[224:227], v[96:99]
	v_mfma_f32_16x16x32_bf16 v[88:91], v[188:191], v[232:235], v[88:91]
	v_mfma_f32_16x16x32_bf16 v[80:83], v[196:199], v[232:235], v[80:83]
	v_mfma_f32_16x16x32_bf16 v[72:75], v[188:191], v[240:243], v[72:75]
	v_mfma_f32_16x16x32_bf16 v[64:67], v[196:199], v[240:243], v[64:67]
	s_setprio 0
	s_barrier
	s_add_i32 s86, s86, s67
	v_lshl_add_u64 v[142:143], s[62:63], 0, v[152:153]
	s_mov_b32 m0, s86
	ds_read_b128 v[210:213], v148 offset:16384
	ds_read_b128 v[214:217], v148 offset:17408
	ds_read_b128 v[218:221], v148 offset:18432
	ds_read_b128 v[224:227], v148 offset:19456
	ds_read_b128 v[228:231], v148 offset:20480
	ds_read_b128 v[232:235], v148 offset:21504
	ds_read_b128 v[236:239], v148 offset:22528
	ds_read_b128 v[240:243], v148 offset:23552
	global_load_lds_dwordx4 v[142:143], off
	s_add_i32 m0, s86, 0x2000
	s_add_u32 s86, s62, 0x40000
	v_lshl_add_u64 v[150:151], s[62:63], 0, v[128:129]
	s_addc_u32 s87, s63, 0
	s_add_i32 s92, s92, s67
	global_load_lds_dwordx4 v[150:151], off
	v_lshl_add_u64 v[244:245], s[86:87], 0, v[152:153]
	s_mov_b32 m0, s92
	v_lshl_add_u64 v[246:247], vcc, 0, v[130:131]
	global_load_lds_dwordx4 v[244:245], off
	v_lshl_add_u64 v[244:245], s[86:87], 0, v[128:129]
	s_add_i32 m0, s92, 0x2000
	s_nop 0
	global_load_lds_dwordx4 v[244:245], off
	v_lshl_add_u64 v[244:245], vcc, 0, v[132:133]
	s_mov_b32 m0, s68
	s_nop 0
	global_load_lds_dwordx4 v[244:245], off
	s_mov_b32 m0, s69
	s_nop 0
	global_load_lds_dwordx4 v[246:247], off
	s_waitcnt vmcnt(8)
	s_waitcnt lgkmcnt(0)
	s_barrier
	s_setprio 1
	s_waitcnt lgkmcnt(0)
	v_mfma_f32_16x16x32_bf16 v[60:63], v[138:141], v[210:213], 0
	v_mfma_f32_16x16x32_bf16 v[52:55], v[176:179], v[210:213], 0
	v_mfma_f32_16x16x32_bf16 v[44:47], v[138:141], v[218:221], 0
	v_mfma_f32_16x16x32_bf16 v[36:39], v[176:179], v[218:221], 0
	v_mfma_f32_16x16x32_bf16 v[28:31], v[138:141], v[228:231], 0
	v_mfma_f32_16x16x32_bf16 v[20:23], v[176:179], v[228:231], 0
	v_mfma_f32_16x16x32_bf16 v[12:15], v[138:141], v[236:239], 0
	v_mfma_f32_16x16x32_bf16 v[4:7], v[176:179], v[236:239], 0
	v_mfma_f32_16x16x32_bf16 v[60:63], v[172:175], v[214:217], v[60:63]
	v_mfma_f32_16x16x32_bf16 v[52:55], v[180:183], v[214:217], v[52:55]
	v_mfma_f32_16x16x32_bf16 v[44:47], v[172:175], v[224:227], v[44:47]
	v_mfma_f32_16x16x32_bf16 v[36:39], v[180:183], v[224:227], v[36:39]
	v_mfma_f32_16x16x32_bf16 v[28:31], v[172:175], v[232:235], v[28:31]
	v_mfma_f32_16x16x32_bf16 v[20:23], v[180:183], v[232:235], v[20:23]
	v_mfma_f32_16x16x32_bf16 v[12:15], v[172:175], v[240:243], v[12:15]
	v_mfma_f32_16x16x32_bf16 v[4:7], v[180:183], v[240:243], v[4:7]
	s_setprio 0
	s_setprio 1
	v_mfma_f32_16x16x32_bf16 v[56:59], v[184:187], v[210:213], 0
	v_mfma_f32_16x16x32_bf16 v[48:51], v[192:195], v[210:213], 0
	v_mfma_f32_16x16x32_bf16 v[40:43], v[184:187], v[218:221], 0
	v_mfma_f32_16x16x32_bf16 v[32:35], v[192:195], v[218:221], 0
	v_mfma_f32_16x16x32_bf16 v[24:27], v[184:187], v[228:231], 0
	v_mfma_f32_16x16x32_bf16 v[16:19], v[192:195], v[228:231], 0
	v_mfma_f32_16x16x32_bf16 v[8:11], v[184:187], v[236:239], 0
	v_mfma_f32_16x16x32_bf16 v[0:3], v[192:195], v[236:239], 0
	v_mfma_f32_16x16x32_bf16 v[56:59], v[188:191], v[214:217], v[56:59]
	v_mfma_f32_16x16x32_bf16 v[48:51], v[196:199], v[214:217], v[48:51]
	v_mfma_f32_16x16x32_bf16 v[40:43], v[188:191], v[224:227], v[40:43]
	v_mfma_f32_16x16x32_bf16 v[32:35], v[196:199], v[224:227], v[32:35]
	v_mfma_f32_16x16x32_bf16 v[24:27], v[188:191], v[232:235], v[24:27]
	v_mfma_f32_16x16x32_bf16 v[16:19], v[196:199], v[232:235], v[16:19]
	v_mfma_f32_16x16x32_bf16 v[8:11], v[188:191], v[240:243], v[8:11]
	v_mfma_f32_16x16x32_bf16 v[0:3], v[196:199], v[240:243], v[0:3]
	s_setprio 0
	s_barrier
	s_add_i32 s92, 0, 0x18000
	v_add_u32_e32 v149, s92, v145
	s_add_i32 s93, 0, 0x1c000
	ds_read_b128 v[138:141], v149
	ds_read_b128 v[172:175], v149 offset:1024
	ds_read_b128 v[176:179], v149 offset:2048
	ds_read_b128 v[180:183], v149 offset:3072
	v_add_u32_e32 v149, s93, v145
	ds_read_b128 v[184:187], v149
	ds_read_b128 v[188:191], v149 offset:1024
	ds_read_b128 v[192:195], v149 offset:2048
	ds_read_b128 v[196:199], v149 offset:3072
	s_add_u32 s86, vcc_lo, 0x40000
	s_addc_u32 s87, vcc_hi, 0
	s_mov_b32 m0, s74
	v_lshl_add_u64 v[248:249], s[86:87], 0, v[132:133]
	ds_read_b128 v[210:213], v148 offset:32768
	ds_read_b128 v[214:217], v148 offset:33792
	ds_read_b128 v[218:221], v148 offset:34816
	ds_read_b128 v[224:227], v148 offset:35840
	ds_read_b128 v[228:231], v148 offset:36864
	ds_read_b128 v[232:235], v148 offset:37888
	ds_read_b128 v[236:239], v148 offset:38912
	ds_read_b128 v[240:243], v148 offset:39936
	global_load_lds_dwordx4 v[248:249], off
	v_lshl_add_u64 v[248:249], s[86:87], 0, v[130:131]
	s_mov_b32 m0, s75
	s_nop 0
	global_load_lds_dwordx4 v[248:249], off
	s_waitcnt vmcnt(8)
	s_waitcnt lgkmcnt(0)
	s_barrier
	s_setprio 1
	s_waitcnt lgkmcnt(0)
	v_mfma_f32_16x16x32_bf16 v[124:127], v[138:141], v[210:213], v[124:127]
	v_mfma_f32_16x16x32_bf16 v[116:119], v[176:179], v[210:213], v[116:119]
	v_mfma_f32_16x16x32_bf16 v[108:111], v[138:141], v[218:221], v[108:111]
	v_mfma_f32_16x16x32_bf16 v[100:103], v[176:179], v[218:221], v[100:103]
	v_mfma_f32_16x16x32_bf16 v[92:95], v[138:141], v[228:231], v[92:95]
	v_mfma_f32_16x16x32_bf16 v[84:87], v[176:179], v[228:231], v[84:87]
	v_mfma_f32_16x16x32_bf16 v[76:79], v[138:141], v[236:239], v[76:79]
	v_mfma_f32_16x16x32_bf16 v[68:71], v[176:179], v[236:239], v[68:71]
	v_mfma_f32_16x16x32_bf16 v[124:127], v[172:175], v[214:217], v[124:127]
	v_mfma_f32_16x16x32_bf16 v[116:119], v[180:183], v[214:217], v[116:119]
	v_mfma_f32_16x16x32_bf16 v[108:111], v[172:175], v[224:227], v[108:111]
	v_mfma_f32_16x16x32_bf16 v[100:103], v[180:183], v[224:227], v[100:103]
	v_mfma_f32_16x16x32_bf16 v[92:95], v[172:175], v[232:235], v[92:95]
	v_mfma_f32_16x16x32_bf16 v[84:87], v[180:183], v[232:235], v[84:87]
	v_mfma_f32_16x16x32_bf16 v[76:79], v[172:175], v[240:243], v[76:79]
	v_mfma_f32_16x16x32_bf16 v[68:71], v[180:183], v[240:243], v[68:71]
	s_setprio 0
	s_setprio 1
	v_mfma_f32_16x16x32_bf16 v[120:123], v[184:187], v[210:213], v[120:123]
	v_mfma_f32_16x16x32_bf16 v[112:115], v[192:195], v[210:213], v[112:115]
	v_mfma_f32_16x16x32_bf16 v[104:107], v[184:187], v[218:221], v[104:107]
	v_mfma_f32_16x16x32_bf16 v[96:99], v[192:195], v[218:221], v[96:99]
	v_mfma_f32_16x16x32_bf16 v[88:91], v[184:187], v[228:231], v[88:91]
	v_mfma_f32_16x16x32_bf16 v[80:83], v[192:195], v[228:231], v[80:83]
	v_mfma_f32_16x16x32_bf16 v[72:75], v[184:187], v[236:239], v[72:75]
	v_mfma_f32_16x16x32_bf16 v[64:67], v[192:195], v[236:239], v[64:67]
	v_mfma_f32_16x16x32_bf16 v[120:123], v[188:191], v[214:217], v[120:123]
	v_mfma_f32_16x16x32_bf16 v[112:115], v[196:199], v[214:217], v[112:115]
	v_mfma_f32_16x16x32_bf16 v[104:107], v[188:191], v[224:227], v[104:107]
	v_mfma_f32_16x16x32_bf16 v[96:99], v[196:199], v[224:227], v[96:99]
	v_mfma_f32_16x16x32_bf16 v[88:91], v[188:191], v[232:235], v[88:91]
	v_mfma_f32_16x16x32_bf16 v[80:83], v[196:199], v[232:235], v[80:83]
	v_mfma_f32_16x16x32_bf16 v[72:75], v[188:191], v[240:243], v[72:75]
	v_mfma_f32_16x16x32_bf16 v[64:67], v[196:199], v[240:243], v[64:67]
	s_setprio 0
	s_barrier
	s_add_i32 s86, s92, s67
	v_lshl_add_u64 v[142:143], v[142:143], 0, s[22:23]
	s_mov_b32 m0, s86
	ds_read_b128 v[210:213], v148 offset:49152
	ds_read_b128 v[214:217], v148 offset:50176
	ds_read_b128 v[218:221], v148 offset:51200
	ds_read_b128 v[224:227], v148 offset:52224
	ds_read_b128 v[228:231], v148 offset:53248
	ds_read_b128 v[232:235], v148 offset:54272
	ds_read_b128 v[236:239], v148 offset:55296
	ds_read_b128 v[240:243], v148 offset:56320
	global_load_lds_dwordx4 v[142:143], off
	s_add_i32 m0, s86, 0x2000
	s_add_u32 s62, s62, 0x40080
	v_lshl_add_u64 v[142:143], v[150:151], 0, s[22:23]
	s_addc_u32 s63, s63, 0
	s_add_i32 s86, s93, s67
	global_load_lds_dwordx4 v[142:143], off
	v_lshl_add_u64 v[142:143], s[62:63], 0, v[152:153]
	s_mov_b32 m0, s86
	s_nop 0
	global_load_lds_dwordx4 v[142:143], off
	v_lshl_add_u64 v[142:143], s[62:63], 0, v[128:129]
	s_add_i32 m0, s86, 0x2000
	s_nop 0
	global_load_lds_dwordx4 v[142:143], off
	v_lshl_add_u64 v[142:143], v[244:245], 0, s[22:23]
	s_mov_b32 m0, s77
	s_nop 0
	global_load_lds_dwordx4 v[142:143], off
	v_lshl_add_u64 v[142:143], v[246:247], 0, s[22:23]
	s_mov_b32 m0, s78
	s_nop 0
	global_load_lds_dwordx4 v[142:143], off
	s_waitcnt vmcnt(8)
	s_waitcnt lgkmcnt(0)
	s_barrier
	s_setprio 1
	s_waitcnt lgkmcnt(0)
	v_mfma_f32_16x16x32_bf16 v[60:63], v[138:141], v[210:213], v[60:63]
	v_mfma_f32_16x16x32_bf16 v[52:55], v[176:179], v[210:213], v[52:55]
	v_mfma_f32_16x16x32_bf16 v[44:47], v[138:141], v[218:221], v[44:47]
	v_mfma_f32_16x16x32_bf16 v[36:39], v[176:179], v[218:221], v[36:39]
	v_mfma_f32_16x16x32_bf16 v[28:31], v[138:141], v[228:231], v[28:31]
	v_mfma_f32_16x16x32_bf16 v[20:23], v[176:179], v[228:231], v[20:23]
	v_mfma_f32_16x16x32_bf16 v[12:15], v[138:141], v[236:239], v[12:15]
	v_mfma_f32_16x16x32_bf16 v[4:7], v[176:179], v[236:239], v[4:7]
	v_mfma_f32_16x16x32_bf16 v[60:63], v[172:175], v[214:217], v[60:63]
	v_mfma_f32_16x16x32_bf16 v[52:55], v[180:183], v[214:217], v[52:55]
	v_mfma_f32_16x16x32_bf16 v[44:47], v[172:175], v[224:227], v[44:47]
	v_mfma_f32_16x16x32_bf16 v[36:39], v[180:183], v[224:227], v[36:39]
	v_mfma_f32_16x16x32_bf16 v[28:31], v[172:175], v[232:235], v[28:31]
	v_mfma_f32_16x16x32_bf16 v[20:23], v[180:183], v[232:235], v[20:23]
	v_mfma_f32_16x16x32_bf16 v[12:15], v[172:175], v[240:243], v[12:15]
	v_mfma_f32_16x16x32_bf16 v[4:7], v[180:183], v[240:243], v[4:7]
	s_setprio 0
	s_setprio 1
	v_mfma_f32_16x16x32_bf16 v[56:59], v[184:187], v[210:213], v[56:59]
	v_mfma_f32_16x16x32_bf16 v[48:51], v[192:195], v[210:213], v[48:51]
	v_mfma_f32_16x16x32_bf16 v[40:43], v[184:187], v[218:221], v[40:43]
	v_mfma_f32_16x16x32_bf16 v[32:35], v[192:195], v[218:221], v[32:35]
	v_mfma_f32_16x16x32_bf16 v[24:27], v[184:187], v[228:231], v[24:27]
	v_mfma_f32_16x16x32_bf16 v[16:19], v[192:195], v[228:231], v[16:19]
	v_mfma_f32_16x16x32_bf16 v[8:11], v[184:187], v[236:239], v[8:11]
	v_mfma_f32_16x16x32_bf16 v[0:3], v[192:195], v[236:239], v[0:3]
	v_mfma_f32_16x16x32_bf16 v[56:59], v[188:191], v[214:217], v[56:59]
	v_mfma_f32_16x16x32_bf16 v[48:51], v[196:199], v[214:217], v[48:51]
	v_mfma_f32_16x16x32_bf16 v[40:43], v[188:191], v[224:227], v[40:43]
	v_mfma_f32_16x16x32_bf16 v[32:35], v[196:199], v[224:227], v[32:35]
	v_mfma_f32_16x16x32_bf16 v[24:27], v[188:191], v[232:235], v[24:27]
	v_mfma_f32_16x16x32_bf16 v[16:19], v[196:199], v[232:235], v[16:19]
	v_mfma_f32_16x16x32_bf16 v[8:11], v[188:191], v[240:243], v[8:11]
	v_mfma_f32_16x16x32_bf16 v[0:3], v[196:199], v[240:243], v[0:3]
	s_setprio 0
	s_barrier
	s_add_i32 s85, s85, 2
	s_add_u32 s89, s89, 0x100
	s_addc_u32 s84, s84, 0
	s_add_u32 s60, s60, 0x100
	s_addc_u32 s61, s61, 0
	s_cmp_gt_u32 s85, 13

.LBB0_270:
	s_waitcnt lgkmcnt(0)
	s_add_i32 s87, 0, 0x10000
	s_add_i32 s92, 0, 0x14000
	v_add_u32_e32 v140, s87, v210
	v_add_u32_e32 v186, s92, v210
	ds_read_b128 v[128:131], v140
	ds_read_b128 v[132:135], v140 offset:1024
	ds_read_b128 v[136:139], v140 offset:2048
	ds_read_b128 v[140:143], v140 offset:3072
	ds_read_b128 v[144:147], v186
	ds_read_b128 v[148:151], v186 offset:1024
	ds_read_b128 v[182:185], v186 offset:2048
	ds_read_b128 v[186:189], v186 offset:3072
	ds_read_b128 v[190:193], v212
	ds_read_b128 v[194:197], v212 offset:1024
	ds_read_b128 v[214:217], v212 offset:2048
	ds_read_b128 v[218:221], v212 offset:3072
	ds_read_b128 v[224:227], v212 offset:4096
	ds_read_b128 v[228:231], v212 offset:5120
	ds_read_b128 v[232:235], v212 offset:6144
	ds_read_b128 v[236:239], v212 offset:7168
	s_add_i32 s77, s77, 1
	s_mul_i32 s44, s77, s33
	s_mul_hi_u32 s45, s77, s94
	s_add_i32 s45, s45, s44
	s_mul_i32 s44, s77, s94
	s_add_u32 s44, s44, s2
	s_addc_u32 s45, s45, s3
	v_cmp_gt_i64_e32 vcc, s[44:45], v[164:165]
	v_cmp_lt_i64_e64 s[50:51], s[44:45], v[162:163]
	s_cbranch_vccnz .LBB0_276
	s_ashr_i32 s45, s44, 31
	s_lshr_b32 s45, s45, 29
	s_add_i32 s48, s44, s45
	s_and_b32 s45, s48, -8
	s_sub_i32 s49, s44, s45
	s_cmp_gt_i32 s49, -1
	s_mov_b64 s[44:45], -1
	s_cbranch_scc0 .LBB0_273
	s_lshl_b32 s66, s49, 6
	s_mov_b64 s[44:45], 0

.LBB0_275:
	s_ashr_i32 s44, s48, 3
	s_add_i32 s44, s66, s44
	s_ashr_i32 s45, s44, 31
	s_lshr_b32 s45, s45, 27
	s_add_i32 s45, s44, s45
	s_ashr_i32 s48, s45, 5
	s_lshl_b32 s48, s48, 3
	s_sub_i32 s49, 0x80, s48
	s_min_i32 s49, s49, 8
	s_andn2_b32 s45, s45, 31
	s_sub_i32 s44, s44, s45
	s_lshr_b32 s81, s44, 3
	s_and_b32 s44, s44, 7
	s_add_i32 s82, s48, s44

.LBB0_280:
	s_add_u32 s84, s18, 0x100
	s_addc_u32 s85, s19, 0
	s_mov_b32 s86, -2
	s_add_u32 vcc_lo, s60, 0x100
	s_addc_u32 vcc_hi, s61, 0
	s_cmp_eq_u32 s86, 40
	s_cselect_b32 s67, s51, vcc_hi
	s_cselect_b32 s66, s50, vcc_lo
	s_cselect_b32 s19, s45, s85
	s_cselect_b32 s18, s44, s84
	v_lshl_add_u64 v[198:199], s[60:61], 0, v[180:181]
	s_add_i32 m0, s69, 0xc000
	global_load_lds_dwordx4 v[198:199], off
	v_lshl_add_u64 v[198:199], s[60:61], 0, v[178:179]
	s_add_i32 m0, s69, 0xe000
	s_nop 0
	global_load_lds_dwordx4 v[198:199], off
	s_waitcnt vmcnt(8)
	s_waitcnt lgkmcnt(0)
	s_barrier
	s_setprio 1
	s_waitcnt lgkmcnt(0)
	v_mfma_f32_16x16x32_bf16 v[124:127], v[128:131], v[190:193], 0
	v_mfma_f32_16x16x32_bf16 v[120:123], v[136:139], v[190:193], 0
	v_mfma_f32_16x16x32_bf16 v[108:111], v[128:131], v[214:217], 0
	v_mfma_f32_16x16x32_bf16 v[104:107], v[136:139], v[214:217], 0
	v_mfma_f32_16x16x32_bf16 v[92:95], v[128:131], v[224:227], 0
	v_mfma_f32_16x16x32_bf16 v[88:91], v[136:139], v[224:227], 0
	v_mfma_f32_16x16x32_bf16 v[76:79], v[128:131], v[232:235], 0
	v_mfma_f32_16x16x32_bf16 v[72:75], v[136:139], v[232:235], 0
	v_mfma_f32_16x16x32_bf16 v[124:127], v[132:135], v[194:197], v[124:127]
	v_mfma_f32_16x16x32_bf16 v[120:123], v[140:143], v[194:197], v[120:123]
	v_mfma_f32_16x16x32_bf16 v[108:111], v[132:135], v[218:221], v[108:111]
	v_mfma_f32_16x16x32_bf16 v[104:107], v[140:143], v[218:221], v[104:107]
	v_mfma_f32_16x16x32_bf16 v[92:95], v[132:135], v[228:231], v[92:95]
	v_mfma_f32_16x16x32_bf16 v[88:91], v[140:143], v[228:231], v[88:91]
	v_mfma_f32_16x16x32_bf16 v[76:79], v[132:135], v[236:239], v[76:79]
	v_mfma_f32_16x16x32_bf16 v[72:75], v[140:143], v[236:239], v[72:75]
	s_setprio 0
	s_setprio 1
	v_mfma_f32_16x16x32_bf16 v[116:119], v[144:147], v[190:193], 0
	v_mfma_f32_16x16x32_bf16 v[112:115], v[182:185], v[190:193], 0
	v_mfma_f32_16x16x32_bf16 v[100:103], v[144:147], v[214:217], 0
	v_mfma_f32_16x16x32_bf16 v[96:99], v[182:185], v[214:217], 0
	v_mfma_f32_16x16x32_bf16 v[84:87], v[144:147], v[224:227], 0
	v_mfma_f32_16x16x32_bf16 v[80:83], v[182:185], v[224:227], 0
	v_mfma_f32_16x16x32_bf16 v[68:71], v[144:147], v[232:235], 0
	v_mfma_f32_16x16x32_bf16 v[64:67], v[182:185], v[232:235], 0
	v_mfma_f32_16x16x32_bf16 v[116:119], v[148:151], v[194:197], v[116:119]
	v_mfma_f32_16x16x32_bf16 v[112:115], v[186:189], v[194:197], v[112:115]
	v_mfma_f32_16x16x32_bf16 v[100:103], v[148:151], v[218:221], v[100:103]
	v_mfma_f32_16x16x32_bf16 v[96:99], v[186:189], v[218:221], v[96:99]
	v_mfma_f32_16x16x32_bf16 v[84:87], v[148:151], v[228:231], v[84:87]
	v_mfma_f32_16x16x32_bf16 v[80:83], v[186:189], v[228:231], v[80:83]
	v_mfma_f32_16x16x32_bf16 v[68:71], v[148:151], v[236:239], v[68:71]
	v_mfma_f32_16x16x32_bf16 v[64:67], v[186:189], v[236:239], v[64:67]
	s_setprio 0
	s_barrier
	s_add_i32 s60, s87, s68
	v_lshl_add_u64 v[198:199], s[18:19], 0, v[152:153]
	s_mov_b32 m0, s60
	ds_read_b128 v[190:193], v212 offset:16384
	ds_read_b128 v[194:197], v212 offset:17408
	ds_read_b128 v[214:217], v212 offset:18432
	ds_read_b128 v[218:221], v212 offset:19456
	ds_read_b128 v[224:227], v212 offset:20480
	ds_read_b128 v[228:231], v212 offset:21504
	ds_read_b128 v[232:235], v212 offset:22528
	ds_read_b128 v[236:239], v212 offset:23552
	global_load_lds_dwordx4 v[198:199], off
	s_add_i32 m0, s60, 0x2000
	s_add_u32 s60, s18, 0xb0000
	v_lshl_add_u64 v[240:241], s[18:19], 0, v[172:173]
	s_addc_u32 s61, s19, 0
	s_add_i32 s87, s92, s68
	global_load_lds_dwordx4 v[240:241], off
	v_lshl_add_u64 v[242:243], s[60:61], 0, v[152:153]
	s_mov_b32 m0, s87
	v_lshl_add_u64 v[244:245], s[66:67], 0, v[174:175]
	global_load_lds_dwordx4 v[242:243], off
	v_lshl_add_u64 v[242:243], s[60:61], 0, v[172:173]
	s_add_i32 m0, s87, 0x2000
	s_nop 0
	global_load_lds_dwordx4 v[242:243], off
	v_lshl_add_u64 v[242:243], s[66:67], 0, v[176:177]
	s_mov_b32 m0, s69
	s_nop 0
	global_load_lds_dwordx4 v[242:243], off
	s_mov_b32 m0, s74
	s_nop 0
	global_load_lds_dwordx4 v[244:245], off
	s_waitcnt vmcnt(8)
	s_waitcnt lgkmcnt(0)
	s_barrier
	s_setprio 1
	s_waitcnt lgkmcnt(0)
	v_mfma_f32_16x16x32_bf16 v[60:63], v[128:131], v[190:193], 0
	v_mfma_f32_16x16x32_bf16 v[56:59], v[136:139], v[190:193], 0
	v_mfma_f32_16x16x32_bf16 v[44:47], v[128:131], v[214:217], 0
	v_mfma_f32_16x16x32_bf16 v[40:43], v[136:139], v[214:217], 0
	v_mfma_f32_16x16x32_bf16 v[28:31], v[128:131], v[224:227], 0
	v_mfma_f32_16x16x32_bf16 v[24:27], v[136:139], v[224:227], 0
	v_mfma_f32_16x16x32_bf16 v[12:15], v[128:131], v[232:235], 0
	v_mfma_f32_16x16x32_bf16 v[8:11], v[136:139], v[232:235], 0
	v_mfma_f32_16x16x32_bf16 v[60:63], v[132:135], v[194:197], v[60:63]
	v_mfma_f32_16x16x32_bf16 v[56:59], v[140:143], v[194:197], v[56:59]
	v_mfma_f32_16x16x32_bf16 v[44:47], v[132:135], v[218:221], v[44:47]
	v_mfma_f32_16x16x32_bf16 v[40:43], v[140:143], v[218:221], v[40:43]
	v_mfma_f32_16x16x32_bf16 v[28:31], v[132:135], v[228:231], v[28:31]
	v_mfma_f32_16x16x32_bf16 v[24:27], v[140:143], v[228:231], v[24:27]
	v_mfma_f32_16x16x32_bf16 v[12:15], v[132:135], v[236:239], v[12:15]
	v_mfma_f32_16x16x32_bf16 v[8:11], v[140:143], v[236:239], v[8:11]
	s_setprio 0
	s_setprio 1
	v_mfma_f32_16x16x32_bf16 v[52:55], v[144:147], v[190:193], 0
	v_mfma_f32_16x16x32_bf16 v[48:51], v[182:185], v[190:193], 0
	v_mfma_f32_16x16x32_bf16 v[36:39], v[144:147], v[214:217], 0
	v_mfma_f32_16x16x32_bf16 v[32:35], v[182:185], v[214:217], 0
	v_mfma_f32_16x16x32_bf16 v[20:23], v[144:147], v[224:227], 0
	v_mfma_f32_16x16x32_bf16 v[16:19], v[182:185], v[224:227], 0
	v_mfma_f32_16x16x32_bf16 v[4:7], v[144:147], v[232:235], 0
	v_mfma_f32_16x16x32_bf16 v[0:3], v[182:185], v[232:235], 0
	v_mfma_f32_16x16x32_bf16 v[52:55], v[148:151], v[194:197], v[52:55]
	v_mfma_f32_16x16x32_bf16 v[48:51], v[186:189], v[194:197], v[48:51]
	v_mfma_f32_16x16x32_bf16 v[36:39], v[148:151], v[218:221], v[36:39]
	v_mfma_f32_16x16x32_bf16 v[32:35], v[186:189], v[218:221], v[32:35]
	v_mfma_f32_16x16x32_bf16 v[20:23], v[148:151], v[228:231], v[20:23]
	v_mfma_f32_16x16x32_bf16 v[16:19], v[186:189], v[228:231], v[16:19]
	v_mfma_f32_16x16x32_bf16 v[4:7], v[148:151], v[236:239], v[4:7]
	v_mfma_f32_16x16x32_bf16 v[0:3], v[186:189], v[236:239], v[0:3]
	s_setprio 0
	s_barrier
	s_add_i32 s87, 0, 0x18000
	s_add_i32 s92, 0, 0x1c000
	v_add_u32_e32 v140, s87, v210
	v_add_u32_e32 v186, s92, v210
	ds_read_b128 v[128:131], v140
	ds_read_b128 v[132:135], v140 offset:1024
	ds_read_b128 v[136:139], v140 offset:2048
	ds_read_b128 v[140:143], v140 offset:3072
	ds_read_b128 v[144:147], v186
	ds_read_b128 v[148:151], v186 offset:1024
	ds_read_b128 v[182:185], v186 offset:2048
	ds_read_b128 v[186:189], v186 offset:3072
	s_add_u32 s60, s66, 0xb0000
	s_addc_u32 s61, s67, 0
	s_mov_b32 m0, s75
	v_lshl_add_u64 v[246:247], s[60:61], 0, v[176:177]
	ds_read_b128 v[190:193], v212 offset:32768
	ds_read_b128 v[194:197], v212 offset:33792
	ds_read_b128 v[214:217], v212 offset:34816
	ds_read_b128 v[218:221], v212 offset:35840
	ds_read_b128 v[224:227], v212 offset:36864
	ds_read_b128 v[228:231], v212 offset:37888
	ds_read_b128 v[232:235], v212 offset:38912
	ds_read_b128 v[236:239], v212 offset:39936
	global_load_lds_dwordx4 v[246:247], off
	v_lshl_add_u64 v[246:247], s[60:61], 0, v[174:175]
	s_mov_b32 m0, s76
	s_nop 0
	global_load_lds_dwordx4 v[246:247], off
	s_waitcnt vmcnt(8)
	s_waitcnt lgkmcnt(0)
	s_barrier
	s_setprio 1
	s_waitcnt lgkmcnt(0)
	v_mfma_f32_16x16x32_bf16 v[124:127], v[128:131], v[190:193], v[124:127]
	v_mfma_f32_16x16x32_bf16 v[120:123], v[136:139], v[190:193], v[120:123]
	v_mfma_f32_16x16x32_bf16 v[108:111], v[128:131], v[214:217], v[108:111]
	v_mfma_f32_16x16x32_bf16 v[104:107], v[136:139], v[214:217], v[104:107]
	v_mfma_f32_16x16x32_bf16 v[92:95], v[128:131], v[224:227], v[92:95]
	v_mfma_f32_16x16x32_bf16 v[88:91], v[136:139], v[224:227], v[88:91]
	v_mfma_f32_16x16x32_bf16 v[76:79], v[128:131], v[232:235], v[76:79]
	v_mfma_f32_16x16x32_bf16 v[72:75], v[136:139], v[232:235], v[72:75]
	v_mfma_f32_16x16x32_bf16 v[124:127], v[132:135], v[194:197], v[124:127]
	v_mfma_f32_16x16x32_bf16 v[120:123], v[140:143], v[194:197], v[120:123]
	v_mfma_f32_16x16x32_bf16 v[108:111], v[132:135], v[218:221], v[108:111]
	v_mfma_f32_16x16x32_bf16 v[104:107], v[140:143], v[218:221], v[104:107]
	v_mfma_f32_16x16x32_bf16 v[92:95], v[132:135], v[228:231], v[92:95]
	v_mfma_f32_16x16x32_bf16 v[88:91], v[140:143], v[228:231], v[88:91]
	v_mfma_f32_16x16x32_bf16 v[76:79], v[132:135], v[236:239], v[76:79]
	v_mfma_f32_16x16x32_bf16 v[72:75], v[140:143], v[236:239], v[72:75]
	s_setprio 0
	s_setprio 1
	v_mfma_f32_16x16x32_bf16 v[116:119], v[144:147], v[190:193], v[116:119]
	v_mfma_f32_16x16x32_bf16 v[112:115], v[182:185], v[190:193], v[112:115]
	v_mfma_f32_16x16x32_bf16 v[100:103], v[144:147], v[214:217], v[100:103]
	v_mfma_f32_16x16x32_bf16 v[96:99], v[182:185], v[214:217], v[96:99]
	v_mfma_f32_16x16x32_bf16 v[84:87], v[144:147], v[224:227], v[84:87]
	v_mfma_f32_16x16x32_bf16 v[80:83], v[182:185], v[224:227], v[80:83]
	v_mfma_f32_16x16x32_bf16 v[68:71], v[144:147], v[232:235], v[68:71]
	v_mfma_f32_16x16x32_bf16 v[64:67], v[182:185], v[232:235], v[64:67]
	v_mfma_f32_16x16x32_bf16 v[116:119], v[148:151], v[194:197], v[116:119]
	v_mfma_f32_16x16x32_bf16 v[112:115], v[186:189], v[194:197], v[112:115]
	v_mfma_f32_16x16x32_bf16 v[100:103], v[148:151], v[218:221], v[100:103]
	v_mfma_f32_16x16x32_bf16 v[96:99], v[186:189], v[218:221], v[96:99]
	v_mfma_f32_16x16x32_bf16 v[84:87], v[148:151], v[228:231], v[84:87]
	v_mfma_f32_16x16x32_bf16 v[80:83], v[186:189], v[228:231], v[80:83]
	v_mfma_f32_16x16x32_bf16 v[68:71], v[148:151], v[236:239], v[68:71]
	v_mfma_f32_16x16x32_bf16 v[64:67], v[186:189], v[236:239], v[64:67]
	s_setprio 0
	s_barrier
	s_add_i32 s60, s87, s68
	v_lshl_add_u64 v[198:199], v[198:199], 0, s[22:23]
	s_mov_b32 m0, s60
	ds_read_b128 v[190:193], v212 offset:49152
	ds_read_b128 v[194:197], v212 offset:50176
	ds_read_b128 v[214:217], v212 offset:51200
	ds_read_b128 v[218:221], v212 offset:52224
	ds_read_b128 v[224:227], v212 offset:53248
	ds_read_b128 v[228:231], v212 offset:54272
	ds_read_b128 v[232:235], v212 offset:55296
	ds_read_b128 v[236:239], v212 offset:56320
	global_load_lds_dwordx4 v[198:199], off
	s_add_i32 m0, s60, 0x2000
	s_add_u32 s18, s18, 0xb0080
	v_lshl_add_u64 v[198:199], v[240:241], 0, s[22:23]
	s_addc_u32 s19, s19, 0
	s_add_i32 s60, s92, s68
	global_load_lds_dwordx4 v[198:199], off
	v_lshl_add_u64 v[198:199], s[18:19], 0, v[152:153]
	s_mov_b32 m0, s60
	s_nop 0
	global_load_lds_dwordx4 v[198:199], off
	v_lshl_add_u64 v[198:199], s[18:19], 0, v[172:173]
	s_add_i32 m0, s60, 0x2000
	s_nop 0
	global_load_lds_dwordx4 v[198:199], off
	v_lshl_add_u64 v[198:199], v[242:243], 0, s[22:23]
	s_mov_b32 m0, s79
	s_nop 0
	global_load_lds_dwordx4 v[198:199], off
	v_lshl_add_u64 v[198:199], v[244:245], 0, s[22:23]
	s_mov_b32 m0, s80
	s_nop 0
	global_load_lds_dwordx4 v[198:199], off
	s_waitcnt vmcnt(8)
	s_waitcnt lgkmcnt(0)
	s_barrier
	s_setprio 1
	s_waitcnt lgkmcnt(0)
	v_mfma_f32_16x16x32_bf16 v[60:63], v[128:131], v[190:193], v[60:63]
	v_mfma_f32_16x16x32_bf16 v[56:59], v[136:139], v[190:193], v[56:59]
	v_mfma_f32_16x16x32_bf16 v[44:47], v[128:131], v[214:217], v[44:47]
	v_mfma_f32_16x16x32_bf16 v[40:43], v[136:139], v[214:217], v[40:43]
	v_mfma_f32_16x16x32_bf16 v[28:31], v[128:131], v[224:227], v[28:31]
	v_mfma_f32_16x16x32_bf16 v[24:27], v[136:139], v[224:227], v[24:27]
	v_mfma_f32_16x16x32_bf16 v[12:15], v[128:131], v[232:235], v[12:15]
	v_mfma_f32_16x16x32_bf16 v[8:11], v[136:139], v[232:235], v[8:11]
	v_mfma_f32_16x16x32_bf16 v[60:63], v[132:135], v[194:197], v[60:63]
	v_mfma_f32_16x16x32_bf16 v[56:59], v[140:143], v[194:197], v[56:59]
	v_mfma_f32_16x16x32_bf16 v[44:47], v[132:135], v[218:221], v[44:47]
	v_mfma_f32_16x16x32_bf16 v[40:43], v[140:143], v[218:221], v[40:43]
	v_mfma_f32_16x16x32_bf16 v[28:31], v[132:135], v[228:231], v[28:31]
	v_mfma_f32_16x16x32_bf16 v[24:27], v[140:143], v[228:231], v[24:27]
	v_mfma_f32_16x16x32_bf16 v[12:15], v[132:135], v[236:239], v[12:15]
	v_mfma_f32_16x16x32_bf16 v[8:11], v[140:143], v[236:239], v[8:11]
	s_setprio 0
	s_setprio 1
	v_mfma_f32_16x16x32_bf16 v[52:55], v[144:147], v[190:193], v[52:55]
	v_mfma_f32_16x16x32_bf16 v[48:51], v[182:185], v[190:193], v[48:51]
	v_mfma_f32_16x16x32_bf16 v[36:39], v[144:147], v[214:217], v[36:39]
	v_mfma_f32_16x16x32_bf16 v[32:35], v[182:185], v[214:217], v[32:35]
	v_mfma_f32_16x16x32_bf16 v[20:23], v[144:147], v[224:227], v[20:23]
	v_mfma_f32_16x16x32_bf16 v[16:19], v[182:185], v[224:227], v[16:19]
	v_mfma_f32_16x16x32_bf16 v[4:7], v[144:147], v[232:235], v[4:7]
	v_mfma_f32_16x16x32_bf16 v[0:3], v[182:185], v[232:235], v[0:3]
	v_mfma_f32_16x16x32_bf16 v[52:55], v[148:151], v[194:197], v[52:55]
	v_mfma_f32_16x16x32_bf16 v[48:51], v[186:189], v[194:197], v[48:51]
	v_mfma_f32_16x16x32_bf16 v[36:39], v[148:151], v[218:221], v[36:39]
	v_mfma_f32_16x16x32_bf16 v[32:35], v[186:189], v[218:221], v[32:35]
	v_mfma_f32_16x16x32_bf16 v[20:23], v[148:151], v[228:231], v[20:23]
	v_mfma_f32_16x16x32_bf16 v[16:19], v[186:189], v[228:231], v[16:19]
	v_mfma_f32_16x16x32_bf16 v[4:7], v[148:151], v[236:239], v[4:7]
	v_mfma_f32_16x16x32_bf16 v[0:3], v[186:189], v[236:239], v[0:3]
	s_setprio 0
	s_barrier
	s_add_i32 s86, s86, 2
	s_add_u32 s84, s84, 0x100
	s_addc_u32 s85, s85, 0
	s_cmp_gt_u32 s86, 41
	s_mov_b64 s[60:61], vcc

.LBB0_406:
	v_cmp_gt_i64_e32 vcc, s[10:11], v[166:167]
	s_mov_b64 s[16:17], -1
	s_cbranch_vccnz .LBB0_405
	s_ashr_i32 s8, s10, 31
	s_lshr_b32 s8, s8, 29
	s_add_i32 s8, s10, s8
	s_ashr_i32 s16, s8, 3
	s_and_b32 s8, s8, -8
	s_sub_i32 s8, s10, s8
	s_cmp_lt_i32 s8, 0
	s_movk_i32 s17, 0xd1
	s_cselect_b32 s17, s17, 0xd0
	s_mul_i32 s8, s8, s17
	s_add_i32 s8, s8, s16
	s_mul_hi_i32 s16, s8, 0x4ec4ec4f
	s_lshr_b32 s17, s16, 31
	s_ashr_i32 s16, s16, 5
	s_add_i32 s16, s16, s17
	s_lshl_b32 s17, s16, 3
	s_sub_i32 s19, 0x80, s17
	s_min_i32 s19, s19, 8
	s_mulk_i32 s16, 0x68
	s_sub_i32 s8, s8, s16
	s_and_b32 s8, s8, 7
	s_add_i32 s8, s17, s8
	s_cmp_eq_u32 s8, s18
	s_cbranch_scc1 .LBB0_404
	v_lshl_add_u32 v2, s8, 8, v0
	s_waitcnt lgkmcnt(0)
	v_ashrrev_i32_e32 v3, 31, v2
	v_lshlrev_b64 v[2:3], 6, v[2:3]
	v_lshl_add_u64 v[2:3], s[28:29], 0, v[2:3]
	v_lshl_add_u64 v[6:7], v[2:3], 0, v[152:153]
	global_load_dwordx4 v[2:5], v[6:7], off
	s_nop 0
	global_load_dwordx4 v[6:9], v[6:7], off offset:16
	v_cmp_lt_i32_e32 vcc, v206, v205
	s_waitcnt vmcnt(0)
	v_pk_add_f32 v[4:5], v[4:5], v[8:9]
	v_pk_add_f32 v[2:3], v[2:3], v[6:7]
	s_nop 0
	v_add_f32_e32 v2, v2, v3
	v_add_f32_e32 v3, v4, v5
	v_add_f32_e32 v2, v2, v3
	v_cndmask_b32_e32 v3, v204, v206, vcc
	v_lshlrev_b32_e32 v3, 2, v3
	ds_bpermute_b32 v3, v3, v2
	s_and_saveexec_b64 s[16:17], s[46:47]
	s_cbranch_execz .LBB0_403
	s_waitcnt lgkmcnt(0)
	v_add_f32_e32 v2, v2, v3
	v_fmamk_f32 v2, v2, 0x3a800000, v202
	s_mov_b32 s18, 0x800000
	v_cmp_gt_f32_e32 vcc, s18, v2
	v_mul_f32_e32 v3, 0x4b800000, v2
	s_lshl_b32 s18, s8, 7
	v_cndmask_b32_e32 v2, v2, v3, vcc
	v_rsq_f32_e32 v2, v2
	s_and_b32 s18, s18, 0xc00
	v_mul_f32_e32 v3, 0x45800000, v2
	v_cndmask_b32_e32 v2, v2, v3, vcc
	v_add_u32_e32 v3, s18, v1
	ds_write_b32 v3, v2
	s_branch .LBB0_403

.LBB0_416:
	s_add_i32 s83, 0, 0x10000
	s_add_i32 s86, 0, 0x14000
	v_add_u32_e32 v88, s83, v185
	v_add_u32_e32 v182, s86, v185
	ds_read_b128 v[72:75], v88
	ds_read_b128 v[76:79], v88 offset:1024
	ds_read_b128 v[80:83], v88 offset:2048
	ds_read_b128 v[88:91], v88 offset:3072
	ds_read_b128 v[174:177], v182
	ds_read_b128 v[178:181], v182 offset:1024
	ds_read_b128 v[190:193], v182 offset:2048
	ds_read_b128 v[194:197], v182 offset:3072
	ds_read_b128 v[210:213], v188
	ds_read_b128 v[214:217], v188 offset:1024
	ds_read_b128 v[218:221], v188 offset:2048
	ds_read_b128 v[224:227], v188 offset:3072
	ds_read_b128 v[228:231], v188 offset:4096
	ds_read_b128 v[232:235], v188 offset:5120
	ds_read_b128 v[236:239], v188 offset:6144
	ds_read_b128 v[240:243], v188 offset:7168
	s_add_i32 s75, s75, 1
	s_mul_i32 s19, s75, s33
	s_mul_hi_u32 s21, s75, s94
	s_add_i32 s21, s21, s19
	s_mul_i32 s19, s75, s94
	s_add_u32 s50, s19, s2
	s_addc_u32 s51, s21, s3
	v_cmp_gt_i64_e32 vcc, s[50:51], v[166:167]
	v_cmp_lt_i64_e64 s[46:47], s[50:51], v[168:169]
	s_cbranch_vccnz .LBB0_418
	s_ashr_i32 s18, s50, 31
	s_lshr_b32 s18, s18, 29
	s_add_i32 s18, s50, s18
	s_ashr_i32 s19, s18, 3
	s_and_b32 s18, s18, -8
	s_sub_i32 s18, s50, s18
	s_cmp_lt_i32 s18, 0
	s_movk_i32 s20, 0xd1
	s_cselect_b32 s20, s20, 0xd0
	s_mul_i32 s18, s18, s20
	s_add_i32 s18, s18, s19
	s_mul_hi_i32 s19, s18, 0x4ec4ec4f
	s_lshr_b32 s20, s19, 31
	s_ashr_i32 s19, s19, 5
	s_add_i32 s19, s19, s20
	s_lshl_b32 s20, s19, 3
	s_sub_i32 s21, 0x80, s20
	s_min_i32 s21, s21, 8
	s_mulk_i32 s19, 0x68
	s_sub_i32 s19, s18, s19
	s_lshr_b32 s18, s19, 3
	s_and_b32 s19, s19, 7
	s_add_i32 s20, s20, s19
.LBB0_418:
	s_ashr_i32 s21, s20, 31
	s_lshl_b64 s[50:51], s[20:21], 19
	s_add_u32 s50, s26, s50
	s_addc_u32 s51, s27, s51
	s_and_b64 s[60:61], s[46:47], exec
	s_cselect_b32 s21, s51, s45
	s_cselect_b32 s78, s50, s44
	s_ashr_i32 s19, s18, 31
	s_lshl_b64 s[60:61], s[18:19], 19
	v_readlane_b32 s19, v254, 42
	s_add_u32 s60, s19, s60
	v_readlane_b32 s19, v254, 43
	s_addc_u32 s61, s19, s61
	s_and_b64 s[62:63], s[46:47], exec
	s_cselect_b32 s19, s61, s49
	s_cselect_b32 s79, s60, s48
	s_add_u32 s80, s48, 0x100
	s_addc_u32 s81, s49, 0
	s_add_u32 s48, s44, 0x40080
	s_addc_u32 s49, s45, 0
	s_mov_b32 s82, -2
	s_add_u32 s44, s48, 0xfffc0080
	s_addc_u32 s45, s49, -1
	s_cmp_eq_u32 s82, 12
	s_cselect_b32 s63, s21, s45
	s_cselect_b32 s62, s78, s44
	s_cselect_b32 s45, s19, s81
	s_cselect_b32 s44, s79, s80
	v_lshl_add_u64 v[182:183], s[48:49], 0, v[172:173]
	s_add_i32 m0, s59, 0xc000
	global_load_lds_dwordx4 v[182:183], off
	v_lshl_add_u64 v[182:183], s[48:49], 0, v[150:151]
	s_add_i32 m0, s59, 0xe000
	s_nop 0
	global_load_lds_dwordx4 v[182:183], off
	s_waitcnt vmcnt(8)
	s_waitcnt lgkmcnt(0)
	s_barrier
	s_setprio 1
	s_waitcnt lgkmcnt(0)
	v_mfma_f32_16x16x32_bf16 v[140:143], v[72:75], v[210:213], 0
	v_mfma_f32_16x16x32_bf16 v[136:139], v[80:83], v[210:213], 0
	v_mfma_f32_16x16x32_bf16 v[124:127], v[72:75], v[218:221], 0
	v_mfma_f32_16x16x32_bf16 v[120:123], v[80:83], v[218:221], 0
	v_mfma_f32_16x16x32_bf16 v[108:111], v[72:75], v[228:231], 0
	v_mfma_f32_16x16x32_bf16 v[104:107], v[80:83], v[228:231], 0
	v_mfma_f32_16x16x32_bf16 v[92:95], v[72:75], v[236:239], 0
	v_mfma_f32_16x16x32_bf16 v[84:87], v[80:83], v[236:239], 0
	v_mfma_f32_16x16x32_bf16 v[140:143], v[76:79], v[214:217], v[140:143]
	v_mfma_f32_16x16x32_bf16 v[136:139], v[88:91], v[214:217], v[136:139]
	v_mfma_f32_16x16x32_bf16 v[124:127], v[76:79], v[224:227], v[124:127]
	v_mfma_f32_16x16x32_bf16 v[120:123], v[88:91], v[224:227], v[120:123]
	v_mfma_f32_16x16x32_bf16 v[108:111], v[76:79], v[232:235], v[108:111]
	v_mfma_f32_16x16x32_bf16 v[104:107], v[88:91], v[232:235], v[104:107]
	v_mfma_f32_16x16x32_bf16 v[92:95], v[76:79], v[240:243], v[92:95]
	v_mfma_f32_16x16x32_bf16 v[84:87], v[88:91], v[240:243], v[84:87]
	s_setprio 0
	s_setprio 1
	v_mfma_f32_16x16x32_bf16 v[132:135], v[174:177], v[210:213], 0
	v_mfma_f32_16x16x32_bf16 v[128:131], v[190:193], v[210:213], 0
	v_mfma_f32_16x16x32_bf16 v[116:119], v[174:177], v[218:221], 0
	v_mfma_f32_16x16x32_bf16 v[112:115], v[190:193], v[218:221], 0
	v_mfma_f32_16x16x32_bf16 v[100:103], v[174:177], v[228:231], 0
	v_mfma_f32_16x16x32_bf16 v[96:99], v[190:193], v[228:231], 0
	v_mfma_f32_16x16x32_bf16 v[68:71], v[174:177], v[236:239], 0
	v_mfma_f32_16x16x32_bf16 v[64:67], v[190:193], v[236:239], 0
	v_mfma_f32_16x16x32_bf16 v[132:135], v[178:181], v[214:217], v[132:135]
	v_mfma_f32_16x16x32_bf16 v[128:131], v[194:197], v[214:217], v[128:131]
	v_mfma_f32_16x16x32_bf16 v[116:119], v[178:181], v[224:227], v[116:119]
	v_mfma_f32_16x16x32_bf16 v[112:115], v[194:197], v[224:227], v[112:115]
	v_mfma_f32_16x16x32_bf16 v[100:103], v[178:181], v[232:235], v[100:103]
	v_mfma_f32_16x16x32_bf16 v[96:99], v[194:197], v[232:235], v[96:99]
	v_mfma_f32_16x16x32_bf16 v[68:71], v[178:181], v[240:243], v[68:71]
	v_mfma_f32_16x16x32_bf16 v[64:67], v[194:197], v[240:243], v[64:67]
	s_setprio 0
	s_barrier
	s_add_i32 s83, s83, s8
	v_lshl_add_u64 v[182:183], s[44:45], 0, v[152:153]
	s_mov_b32 m0, s83
	ds_read_b128 v[210:213], v188 offset:16384
	ds_read_b128 v[214:217], v188 offset:17408
	ds_read_b128 v[218:221], v188 offset:18432
	ds_read_b128 v[224:227], v188 offset:19456
	ds_read_b128 v[228:231], v188 offset:20480
	ds_read_b128 v[232:235], v188 offset:21504
	ds_read_b128 v[236:239], v188 offset:22528
	ds_read_b128 v[240:243], v188 offset:23552
	global_load_lds_dwordx4 v[182:183], off
	s_add_i32 m0, s83, 0x2000
	s_add_u32 s84, s44, 0x40000
	v_lshl_add_u64 v[198:199], s[44:45], 0, v[144:145]
	s_addc_u32 s85, s45, 0
	s_add_i32 s83, s86, s8
	global_load_lds_dwordx4 v[198:199], off
	v_lshl_add_u64 v[244:245], s[84:85], 0, v[152:153]
	s_mov_b32 m0, s83
	v_lshl_add_u64 v[246:247], s[62:63], 0, v[146:147]
	global_load_lds_dwordx4 v[244:245], off
	v_lshl_add_u64 v[244:245], s[84:85], 0, v[144:145]
	s_add_i32 m0, s83, 0x2000
	s_nop 0
	global_load_lds_dwordx4 v[244:245], off
	v_lshl_add_u64 v[244:245], s[62:63], 0, v[148:149]
	s_mov_b32 m0, s59
	s_nop 0
	global_load_lds_dwordx4 v[244:245], off
	s_mov_b32 m0, s66
	s_nop 0
	global_load_lds_dwordx4 v[246:247], off
	s_waitcnt vmcnt(8)
	s_waitcnt lgkmcnt(0)
	s_barrier
	s_setprio 1
	s_waitcnt lgkmcnt(0)
	v_mfma_f32_16x16x32_bf16 v[60:63], v[72:75], v[210:213], 0
	v_mfma_f32_16x16x32_bf16 v[56:59], v[80:83], v[210:213], 0
	v_mfma_f32_16x16x32_bf16 v[44:47], v[72:75], v[218:221], 0
	v_mfma_f32_16x16x32_bf16 v[40:43], v[80:83], v[218:221], 0
	v_mfma_f32_16x16x32_bf16 v[28:31], v[72:75], v[228:231], 0
	v_mfma_f32_16x16x32_bf16 v[24:27], v[80:83], v[228:231], 0
	v_mfma_f32_16x16x32_bf16 v[12:15], v[72:75], v[236:239], 0
	v_mfma_f32_16x16x32_bf16 v[8:11], v[80:83], v[236:239], 0
	v_mfma_f32_16x16x32_bf16 v[60:63], v[76:79], v[214:217], v[60:63]
	v_mfma_f32_16x16x32_bf16 v[56:59], v[88:91], v[214:217], v[56:59]
	v_mfma_f32_16x16x32_bf16 v[44:47], v[76:79], v[224:227], v[44:47]
	v_mfma_f32_16x16x32_bf16 v[40:43], v[88:91], v[224:227], v[40:43]
	v_mfma_f32_16x16x32_bf16 v[28:31], v[76:79], v[232:235], v[28:31]
	v_mfma_f32_16x16x32_bf16 v[24:27], v[88:91], v[232:235], v[24:27]
	v_mfma_f32_16x16x32_bf16 v[12:15], v[76:79], v[240:243], v[12:15]
	v_mfma_f32_16x16x32_bf16 v[8:11], v[88:91], v[240:243], v[8:11]
	s_setprio 0
	s_setprio 1
	v_mfma_f32_16x16x32_bf16 v[52:55], v[174:177], v[210:213], 0
	v_mfma_f32_16x16x32_bf16 v[48:51], v[190:193], v[210:213], 0
	v_mfma_f32_16x16x32_bf16 v[36:39], v[174:177], v[218:221], 0
	v_mfma_f32_16x16x32_bf16 v[32:35], v[190:193], v[218:221], 0
	v_mfma_f32_16x16x32_bf16 v[20:23], v[174:177], v[228:231], 0
	v_mfma_f32_16x16x32_bf16 v[16:19], v[190:193], v[228:231], 0
	v_mfma_f32_16x16x32_bf16 v[4:7], v[174:177], v[236:239], 0
	v_mfma_f32_16x16x32_bf16 v[0:3], v[190:193], v[236:239], 0
	v_mfma_f32_16x16x32_bf16 v[52:55], v[178:181], v[214:217], v[52:55]
	v_mfma_f32_16x16x32_bf16 v[48:51], v[194:197], v[214:217], v[48:51]
	v_mfma_f32_16x16x32_bf16 v[36:39], v[178:181], v[224:227], v[36:39]
	v_mfma_f32_16x16x32_bf16 v[32:35], v[194:197], v[224:227], v[32:35]
	v_mfma_f32_16x16x32_bf16 v[20:23], v[178:181], v[232:235], v[20:23]
	v_mfma_f32_16x16x32_bf16 v[16:19], v[194:197], v[232:235], v[16:19]
	v_mfma_f32_16x16x32_bf16 v[4:7], v[178:181], v[240:243], v[4:7]
	v_mfma_f32_16x16x32_bf16 v[0:3], v[194:197], v[240:243], v[0:3]
	s_setprio 0
	s_barrier
	s_add_i32 s83, 0, 0x18000
	s_add_i32 s84, 0, 0x1c000
	v_add_u32_e32 v88, s83, v185
	v_add_u32_e32 v189, s84, v185
	ds_read_b128 v[72:75], v88
	ds_read_b128 v[76:79], v88 offset:1024
	ds_read_b128 v[80:83], v88 offset:2048
	ds_read_b128 v[88:91], v88 offset:3072
	ds_read_b128 v[174:177], v189
	ds_read_b128 v[178:181], v189 offset:1024
	ds_read_b128 v[190:193], v189 offset:2048
	ds_read_b128 v[194:197], v189 offset:3072
	s_add_u32 s62, s62, 0x40000
	s_addc_u32 s63, s63, 0
	s_mov_b32 m0, s67
	v_lshl_add_u64 v[248:249], s[62:63], 0, v[148:149]
	ds_read_b128 v[210:213], v188 offset:32768
	ds_read_b128 v[214:217], v188 offset:33792
	ds_read_b128 v[218:221], v188 offset:34816
	ds_read_b128 v[224:227], v188 offset:35840
	ds_read_b128 v[228:231], v188 offset:36864
	ds_read_b128 v[232:235], v188 offset:37888
	ds_read_b128 v[236:239], v188 offset:38912
	ds_read_b128 v[240:243], v188 offset:39936
	global_load_lds_dwordx4 v[248:249], off
	v_lshl_add_u64 v[248:249], s[62:63], 0, v[146:147]
	s_mov_b32 m0, s68
	s_nop 0
	global_load_lds_dwordx4 v[248:249], off
	s_waitcnt vmcnt(8)
	s_waitcnt lgkmcnt(0)
	s_barrier
	s_setprio 1
	s_waitcnt lgkmcnt(0)
	v_mfma_f32_16x16x32_bf16 v[140:143], v[72:75], v[210:213], v[140:143]
	v_mfma_f32_16x16x32_bf16 v[136:139], v[80:83], v[210:213], v[136:139]
	v_mfma_f32_16x16x32_bf16 v[124:127], v[72:75], v[218:221], v[124:127]
	v_mfma_f32_16x16x32_bf16 v[120:123], v[80:83], v[218:221], v[120:123]
	v_mfma_f32_16x16x32_bf16 v[108:111], v[72:75], v[228:231], v[108:111]
	v_mfma_f32_16x16x32_bf16 v[104:107], v[80:83], v[228:231], v[104:107]
	v_mfma_f32_16x16x32_bf16 v[92:95], v[72:75], v[236:239], v[92:95]
	v_mfma_f32_16x16x32_bf16 v[84:87], v[80:83], v[236:239], v[84:87]
	v_mfma_f32_16x16x32_bf16 v[140:143], v[76:79], v[214:217], v[140:143]
	v_mfma_f32_16x16x32_bf16 v[136:139], v[88:91], v[214:217], v[136:139]
	v_mfma_f32_16x16x32_bf16 v[124:127], v[76:79], v[224:227], v[124:127]
	v_mfma_f32_16x16x32_bf16 v[120:123], v[88:91], v[224:227], v[120:123]
	v_mfma_f32_16x16x32_bf16 v[108:111], v[76:79], v[232:235], v[108:111]
	v_mfma_f32_16x16x32_bf16 v[104:107], v[88:91], v[232:235], v[104:107]
	v_mfma_f32_16x16x32_bf16 v[92:95], v[76:79], v[240:243], v[92:95]
	v_mfma_f32_16x16x32_bf16 v[84:87], v[88:91], v[240:243], v[84:87]
	s_setprio 0
	s_setprio 1
	v_mfma_f32_16x16x32_bf16 v[132:135], v[174:177], v[210:213], v[132:135]
	v_mfma_f32_16x16x32_bf16 v[128:131], v[190:193], v[210:213], v[128:131]
	v_mfma_f32_16x16x32_bf16 v[116:119], v[174:177], v[218:221], v[116:119]
	v_mfma_f32_16x16x32_bf16 v[112:115], v[190:193], v[218:221], v[112:115]
	v_mfma_f32_16x16x32_bf16 v[100:103], v[174:177], v[228:231], v[100:103]
	v_mfma_f32_16x16x32_bf16 v[96:99], v[190:193], v[228:231], v[96:99]
	v_mfma_f32_16x16x32_bf16 v[68:71], v[174:177], v[236:239], v[68:71]
	v_mfma_f32_16x16x32_bf16 v[64:67], v[190:193], v[236:239], v[64:67]
	v_mfma_f32_16x16x32_bf16 v[132:135], v[178:181], v[214:217], v[132:135]
	v_mfma_f32_16x16x32_bf16 v[128:131], v[194:197], v[214:217], v[128:131]
	v_mfma_f32_16x16x32_bf16 v[116:119], v[178:181], v[224:227], v[116:119]
	v_mfma_f32_16x16x32_bf16 v[112:115], v[194:197], v[224:227], v[112:115]
	v_mfma_f32_16x16x32_bf16 v[100:103], v[178:181], v[232:235], v[100:103]
	v_mfma_f32_16x16x32_bf16 v[96:99], v[194:197], v[232:235], v[96:99]
	v_mfma_f32_16x16x32_bf16 v[68:71], v[178:181], v[240:243], v[68:71]
	v_mfma_f32_16x16x32_bf16 v[64:67], v[194:197], v[240:243], v[64:67]
	s_setprio 0
	s_barrier
	s_add_i32 s62, s83, s8
	v_lshl_add_u64 v[182:183], v[182:183], 0, s[22:23]
	s_mov_b32 m0, s62
	ds_read_b128 v[210:213], v188 offset:49152
	ds_read_b128 v[214:217], v188 offset:50176
	ds_read_b128 v[218:221], v188 offset:51200
	ds_read_b128 v[224:227], v188 offset:52224
	ds_read_b128 v[228:231], v188 offset:53248
	ds_read_b128 v[232:235], v188 offset:54272
	ds_read_b128 v[236:239], v188 offset:55296
	ds_read_b128 v[240:243], v188 offset:56320
	global_load_lds_dwordx4 v[182:183], off
	s_add_i32 m0, s62, 0x2000
	s_add_u32 s44, s44, 0x40080
	v_lshl_add_u64 v[182:183], v[198:199], 0, s[22:23]
	s_addc_u32 s45, s45, 0
	s_add_i32 s62, s84, s8
	global_load_lds_dwordx4 v[182:183], off
	v_lshl_add_u64 v[182:183], s[44:45], 0, v[152:153]
	s_mov_b32 m0, s62
	s_nop 0
	global_load_lds_dwordx4 v[182:183], off
	v_lshl_add_u64 v[182:183], s[44:45], 0, v[144:145]
	s_add_i32 m0, s62, 0x2000
	s_nop 0
	global_load_lds_dwordx4 v[182:183], off
	v_lshl_add_u64 v[182:183], v[244:245], 0, s[22:23]
	s_mov_b32 m0, s69
	s_nop 0
	global_load_lds_dwordx4 v[182:183], off
	v_lshl_add_u64 v[182:183], v[246:247], 0, s[22:23]
	s_mov_b32 m0, s74
	s_nop 0
	global_load_lds_dwordx4 v[182:183], off
	s_waitcnt vmcnt(8)
	s_waitcnt lgkmcnt(0)
	s_barrier
	s_setprio 1
	s_waitcnt lgkmcnt(0)
	v_mfma_f32_16x16x32_bf16 v[60:63], v[72:75], v[210:213], v[60:63]
	v_mfma_f32_16x16x32_bf16 v[56:59], v[80:83], v[210:213], v[56:59]
	v_mfma_f32_16x16x32_bf16 v[44:47], v[72:75], v[218:221], v[44:47]
	v_mfma_f32_16x16x32_bf16 v[40:43], v[80:83], v[218:221], v[40:43]
	v_mfma_f32_16x16x32_bf16 v[28:31], v[72:75], v[228:231], v[28:31]
	v_mfma_f32_16x16x32_bf16 v[24:27], v[80:83], v[228:231], v[24:27]
	v_mfma_f32_16x16x32_bf16 v[12:15], v[72:75], v[236:239], v[12:15]
	v_mfma_f32_16x16x32_bf16 v[8:11], v[80:83], v[236:239], v[8:11]
	v_mfma_f32_16x16x32_bf16 v[60:63], v[76:79], v[214:217], v[60:63]
	v_mfma_f32_16x16x32_bf16 v[56:59], v[88:91], v[214:217], v[56:59]
	v_mfma_f32_16x16x32_bf16 v[44:47], v[76:79], v[224:227], v[44:47]
	v_mfma_f32_16x16x32_bf16 v[40:43], v[88:91], v[224:227], v[40:43]
	v_mfma_f32_16x16x32_bf16 v[28:31], v[76:79], v[232:235], v[28:31]
	v_mfma_f32_16x16x32_bf16 v[24:27], v[88:91], v[232:235], v[24:27]
	v_mfma_f32_16x16x32_bf16 v[12:15], v[76:79], v[240:243], v[12:15]
	v_mfma_f32_16x16x32_bf16 v[8:11], v[88:91], v[240:243], v[8:11]
	s_setprio 0
	s_setprio 1
	v_mfma_f32_16x16x32_bf16 v[52:55], v[174:177], v[210:213], v[52:55]
	v_mfma_f32_16x16x32_bf16 v[48:51], v[190:193], v[210:213], v[48:51]
	v_mfma_f32_16x16x32_bf16 v[36:39], v[174:177], v[218:221], v[36:39]
	v_mfma_f32_16x16x32_bf16 v[32:35], v[190:193], v[218:221], v[32:35]
	v_mfma_f32_16x16x32_bf16 v[20:23], v[174:177], v[228:231], v[20:23]
	v_mfma_f32_16x16x32_bf16 v[16:19], v[190:193], v[228:231], v[16:19]
	v_mfma_f32_16x16x32_bf16 v[4:7], v[174:177], v[236:239], v[4:7]
	v_mfma_f32_16x16x32_bf16 v[0:3], v[190:193], v[236:239], v[0:3]
	v_mfma_f32_16x16x32_bf16 v[52:55], v[178:181], v[214:217], v[52:55]
	v_mfma_f32_16x16x32_bf16 v[48:51], v[194:197], v[214:217], v[48:51]
	v_mfma_f32_16x16x32_bf16 v[36:39], v[178:181], v[224:227], v[36:39]
	v_mfma_f32_16x16x32_bf16 v[32:35], v[194:197], v[224:227], v[32:35]
	v_mfma_f32_16x16x32_bf16 v[20:23], v[178:181], v[232:235], v[20:23]
	v_mfma_f32_16x16x32_bf16 v[16:19], v[194:197], v[232:235], v[16:19]
	v_mfma_f32_16x16x32_bf16 v[4:7], v[178:181], v[240:243], v[4:7]
	v_mfma_f32_16x16x32_bf16 v[0:3], v[194:197], v[240:243], v[0:3]
	s_setprio 0
	s_barrier
	s_add_i32 s82, s82, 2
	s_add_u32 s80, s80, 0x100
	s_addc_u32 s81, s81, 0
	s_add_u32 s48, s48, 0x100
	s_addc_u32 s49, s49, 0
	s_cmp_gt_u32 s82, 13

.LBB0_698:
	s_add_i32 s83, 0, 0x10000
	s_add_i32 s86, 0, 0x14000
	v_add_u32_e32 v140, s83, v195
	v_add_u32_e32 v186, s86, v195
	ds_read_b128 v[124:127], v140
	ds_read_b128 v[132:135], v140 offset:1024
	ds_read_b128 v[136:139], v140 offset:2048
	ds_read_b128 v[140:143], v140 offset:3072
	ds_read_b128 v[144:147], v186
	ds_read_b128 v[148:151], v186 offset:1024
	ds_read_b128 v[182:185], v186 offset:2048
	ds_read_b128 v[186:189], v186 offset:3072
	ds_read_b128 v[190:193], v197
	ds_read_b128 v[210:213], v197 offset:1024
	ds_read_b128 v[214:217], v197 offset:2048
	ds_read_b128 v[218:221], v197 offset:3072
	ds_read_b128 v[224:227], v197 offset:4096
	ds_read_b128 v[228:231], v197 offset:5120
	ds_read_b128 v[232:235], v197 offset:6144
	ds_read_b128 v[236:239], v197 offset:7168
	s_add_i32 s75, s75, 1
	s_mul_i32 s19, s75, s33
	s_mul_hi_u32 s21, s75, s94
	s_add_i32 s21, s21, s19
	s_mul_i32 s19, s75, s94
	s_add_u32 s48, s19, s2
	s_addc_u32 s49, s21, s3
	v_cmp_gt_i64_e32 vcc, s[48:49], v[164:165]
	v_cmp_lt_i64_e64 s[46:47], s[48:49], v[162:163]
	s_cbranch_vccnz .LBB0_704
	s_ashr_i32 s18, s48, 31
	s_lshr_b32 s18, s18, 29
	s_add_i32 s20, s48, s18
	s_and_b32 s18, s20, -8
	s_sub_i32 s21, s48, s18
	s_cmp_gt_i32 s21, -1
	s_mov_b64 s[18:19], -1
	s_cbranch_scc0 .LBB0_701
	s_lshl_b32 s48, s21, 6
	s_mov_b64 s[18:19], 0

.LBB0_703:
	s_ashr_i32 s18, s20, 3
	s_add_i32 s18, s48, s18
	s_ashr_i32 s19, s18, 31
	s_lshr_b32 s19, s19, 27
	s_add_i32 s19, s18, s19
	s_ashr_i32 s20, s19, 5
	s_lshl_b32 s20, s20, 3
	s_sub_i32 s21, 0x80, s20
	s_min_i32 s21, s21, 8
	s_andn2_b32 s19, s19, 31
	s_sub_i32 s19, s18, s19
	s_lshr_b32 s18, s19, 3
	s_and_b32 s19, s19, 7
	s_add_i32 s20, s20, s19
.LBB0_704:
	s_ashr_i32 s21, s20, 31
	s_lshl_b64 s[48:49], s[20:21], 18
	v_readlane_b32 s19, v254, 14
	s_add_u32 s48, s19, s48
	v_readlane_b32 s19, v254, 15
	s_addc_u32 s49, s19, s49
	s_and_b64 s[50:51], s[46:47], exec
	s_cselect_b32 s21, s49, s45
	s_cselect_b32 s78, s48, s44
	s_ashr_i32 s19, s18, 31
	s_lshl_b64 s[50:51], s[18:19], 18
	v_readlane_b32 s19, v254, 10
	s_add_u32 s50, s19, s50
	v_readlane_b32 s19, v254, 11
	s_addc_u32 s51, s19, s51
	s_and_b64 s[62:63], s[46:47], exec
	s_cselect_b32 s19, s51, s61
	s_cselect_b32 s79, s50, s60
	s_add_u32 s80, s60, 0x100
	s_addc_u32 s81, s61, 0
	s_add_u32 s60, s44, 0x20080
	s_addc_u32 s61, s45, 0
	s_mov_b32 s82, -2
	s_add_u32 s44, s60, 0xfffe0080
	s_addc_u32 s45, s61, -1
	s_cmp_eq_u32 s82, 4
	s_cselect_b32 s63, s21, s45
	s_cselect_b32 s62, s78, s44
	s_cselect_b32 s45, s19, s81
	s_cselect_b32 s44, s79, s80
	v_lshl_add_u64 v[198:199], s[60:61], 0, v[180:181]
	s_add_i32 m0, s59, 0xc000
	global_load_lds_dwordx4 v[198:199], off
	v_lshl_add_u64 v[198:199], s[60:61], 0, v[178:179]
	s_add_i32 m0, s59, 0xe000
	s_nop 0
	global_load_lds_dwordx4 v[198:199], off
	s_waitcnt vmcnt(8)
	s_waitcnt lgkmcnt(0)
	s_barrier
	s_setprio 1
	s_waitcnt lgkmcnt(0)
	v_mfma_f32_16x16x32_bf16 v[128:131], v[124:127], v[190:193], 0
	v_mfma_f32_16x16x32_bf16 v[120:123], v[136:139], v[190:193], 0
	v_mfma_f32_16x16x32_bf16 v[108:111], v[124:127], v[214:217], 0
	v_mfma_f32_16x16x32_bf16 v[104:107], v[136:139], v[214:217], 0
	v_mfma_f32_16x16x32_bf16 v[92:95], v[124:127], v[224:227], 0
	v_mfma_f32_16x16x32_bf16 v[88:91], v[136:139], v[224:227], 0
	v_mfma_f32_16x16x32_bf16 v[76:79], v[124:127], v[232:235], 0
	v_mfma_f32_16x16x32_bf16 v[72:75], v[136:139], v[232:235], 0
	v_mfma_f32_16x16x32_bf16 v[128:131], v[132:135], v[210:213], v[128:131]
	v_mfma_f32_16x16x32_bf16 v[120:123], v[140:143], v[210:213], v[120:123]
	v_mfma_f32_16x16x32_bf16 v[108:111], v[132:135], v[218:221], v[108:111]
	v_mfma_f32_16x16x32_bf16 v[104:107], v[140:143], v[218:221], v[104:107]
	v_mfma_f32_16x16x32_bf16 v[92:95], v[132:135], v[228:231], v[92:95]
	v_mfma_f32_16x16x32_bf16 v[88:91], v[140:143], v[228:231], v[88:91]
	v_mfma_f32_16x16x32_bf16 v[76:79], v[132:135], v[236:239], v[76:79]
	v_mfma_f32_16x16x32_bf16 v[72:75], v[140:143], v[236:239], v[72:75]
	s_setprio 0
	s_setprio 1
	v_mfma_f32_16x16x32_bf16 v[116:119], v[144:147], v[190:193], 0
	v_mfma_f32_16x16x32_bf16 v[112:115], v[182:185], v[190:193], 0
	v_mfma_f32_16x16x32_bf16 v[100:103], v[144:147], v[214:217], 0
	v_mfma_f32_16x16x32_bf16 v[96:99], v[182:185], v[214:217], 0
	v_mfma_f32_16x16x32_bf16 v[84:87], v[144:147], v[224:227], 0
	v_mfma_f32_16x16x32_bf16 v[80:83], v[182:185], v[224:227], 0
	v_mfma_f32_16x16x32_bf16 v[68:71], v[144:147], v[232:235], 0
	v_mfma_f32_16x16x32_bf16 v[64:67], v[182:185], v[232:235], 0
	v_mfma_f32_16x16x32_bf16 v[116:119], v[148:151], v[210:213], v[116:119]
	v_mfma_f32_16x16x32_bf16 v[112:115], v[186:189], v[210:213], v[112:115]
	v_mfma_f32_16x16x32_bf16 v[100:103], v[148:151], v[218:221], v[100:103]
	v_mfma_f32_16x16x32_bf16 v[96:99], v[186:189], v[218:221], v[96:99]
	v_mfma_f32_16x16x32_bf16 v[84:87], v[148:151], v[228:231], v[84:87]
	v_mfma_f32_16x16x32_bf16 v[80:83], v[186:189], v[228:231], v[80:83]
	v_mfma_f32_16x16x32_bf16 v[68:71], v[148:151], v[236:239], v[68:71]
	v_mfma_f32_16x16x32_bf16 v[64:67], v[186:189], v[236:239], v[64:67]
	s_setprio 0
	s_barrier
	s_add_i32 s83, s83, s8
	v_lshl_add_u64 v[198:199], s[44:45], 0, v[152:153]
	s_mov_b32 m0, s83
	ds_read_b128 v[190:193], v197 offset:16384
	ds_read_b128 v[210:213], v197 offset:17408
	ds_read_b128 v[214:217], v197 offset:18432
	ds_read_b128 v[218:221], v197 offset:19456
	ds_read_b128 v[224:227], v197 offset:20480
	ds_read_b128 v[228:231], v197 offset:21504
	ds_read_b128 v[232:235], v197 offset:22528
	ds_read_b128 v[236:239], v197 offset:23552
	global_load_lds_dwordx4 v[198:199], off
	s_add_i32 m0, s83, 0x2000
	s_add_u32 s84, s44, 0x20000
	v_lshl_add_u64 v[240:241], s[44:45], 0, v[172:173]
	s_addc_u32 s85, s45, 0
	s_add_i32 s83, s86, s8
	global_load_lds_dwordx4 v[240:241], off
	v_lshl_add_u64 v[242:243], s[84:85], 0, v[152:153]
	s_mov_b32 m0, s83
	v_lshl_add_u64 v[244:245], s[62:63], 0, v[174:175]
	global_load_lds_dwordx4 v[242:243], off
	v_lshl_add_u64 v[242:243], s[84:85], 0, v[172:173]
	s_add_i32 m0, s83, 0x2000
	s_nop 0
	global_load_lds_dwordx4 v[242:243], off
	v_lshl_add_u64 v[242:243], s[62:63], 0, v[176:177]
	s_mov_b32 m0, s59
	s_nop 0
	global_load_lds_dwordx4 v[242:243], off
	s_mov_b32 m0, s66
	s_nop 0
	global_load_lds_dwordx4 v[244:245], off
	s_waitcnt vmcnt(8)
	s_waitcnt lgkmcnt(0)
	s_barrier
	s_setprio 1
	s_waitcnt lgkmcnt(0)
	v_mfma_f32_16x16x32_bf16 v[60:63], v[124:127], v[190:193], 0
	v_mfma_f32_16x16x32_bf16 v[56:59], v[136:139], v[190:193], 0
	v_mfma_f32_16x16x32_bf16 v[48:51], v[124:127], v[214:217], 0
	v_mfma_f32_16x16x32_bf16 v[40:43], v[136:139], v[214:217], 0
	v_mfma_f32_16x16x32_bf16 v[32:35], v[124:127], v[224:227], 0
	v_mfma_f32_16x16x32_bf16 v[24:27], v[136:139], v[224:227], 0
	v_mfma_f32_16x16x32_bf16 v[16:19], v[124:127], v[232:235], 0
	v_mfma_f32_16x16x32_bf16 v[8:11], v[136:139], v[232:235], 0
	v_mfma_f32_16x16x32_bf16 v[60:63], v[132:135], v[210:213], v[60:63]
	v_mfma_f32_16x16x32_bf16 v[56:59], v[140:143], v[210:213], v[56:59]
	v_mfma_f32_16x16x32_bf16 v[48:51], v[132:135], v[218:221], v[48:51]
	v_mfma_f32_16x16x32_bf16 v[40:43], v[140:143], v[218:221], v[40:43]
	v_mfma_f32_16x16x32_bf16 v[32:35], v[132:135], v[228:231], v[32:35]
	v_mfma_f32_16x16x32_bf16 v[24:27], v[140:143], v[228:231], v[24:27]
	v_mfma_f32_16x16x32_bf16 v[16:19], v[132:135], v[236:239], v[16:19]
	v_mfma_f32_16x16x32_bf16 v[8:11], v[140:143], v[236:239], v[8:11]
	s_setprio 0
	s_setprio 1
	v_mfma_f32_16x16x32_bf16 v[52:55], v[144:147], v[190:193], 0
	v_mfma_f32_16x16x32_bf16 v[44:47], v[182:185], v[190:193], 0
	v_mfma_f32_16x16x32_bf16 v[36:39], v[144:147], v[214:217], 0
	v_mfma_f32_16x16x32_bf16 v[28:31], v[182:185], v[214:217], 0
	v_mfma_f32_16x16x32_bf16 v[20:23], v[144:147], v[224:227], 0
	v_mfma_f32_16x16x32_bf16 v[12:15], v[182:185], v[224:227], 0
	v_mfma_f32_16x16x32_bf16 v[4:7], v[144:147], v[232:235], 0
	v_mfma_f32_16x16x32_bf16 v[0:3], v[182:185], v[232:235], 0
	v_mfma_f32_16x16x32_bf16 v[52:55], v[148:151], v[210:213], v[52:55]
	v_mfma_f32_16x16x32_bf16 v[44:47], v[186:189], v[210:213], v[44:47]
	v_mfma_f32_16x16x32_bf16 v[36:39], v[148:151], v[218:221], v[36:39]
	v_mfma_f32_16x16x32_bf16 v[28:31], v[186:189], v[218:221], v[28:31]
	v_mfma_f32_16x16x32_bf16 v[20:23], v[148:151], v[228:231], v[20:23]
	v_mfma_f32_16x16x32_bf16 v[12:15], v[186:189], v[228:231], v[12:15]
	v_mfma_f32_16x16x32_bf16 v[4:7], v[148:151], v[236:239], v[4:7]
	v_mfma_f32_16x16x32_bf16 v[0:3], v[186:189], v[236:239], v[0:3]
	s_setprio 0
	s_barrier
	s_add_i32 s83, 0, 0x18000
	s_add_i32 s84, 0, 0x1c000
	v_add_u32_e32 v140, s83, v195
	v_add_u32_e32 v186, s84, v195
	ds_read_b128 v[124:127], v140
	ds_read_b128 v[132:135], v140 offset:1024
	ds_read_b128 v[136:139], v140 offset:2048
	ds_read_b128 v[140:143], v140 offset:3072
	ds_read_b128 v[144:147], v186
	ds_read_b128 v[148:151], v186 offset:1024
	ds_read_b128 v[182:185], v186 offset:2048
	ds_read_b128 v[186:189], v186 offset:3072
	s_add_u32 s62, s62, 0x20000
	s_addc_u32 s63, s63, 0
	s_mov_b32 m0, s67
	v_lshl_add_u64 v[246:247], s[62:63], 0, v[176:177]
	ds_read_b128 v[190:193], v197 offset:32768
	ds_read_b128 v[210:213], v197 offset:33792
	ds_read_b128 v[214:217], v197 offset:34816
	ds_read_b128 v[218:221], v197 offset:35840
	ds_read_b128 v[224:227], v197 offset:36864
	ds_read_b128 v[228:231], v197 offset:37888
	ds_read_b128 v[232:235], v197 offset:38912
	ds_read_b128 v[236:239], v197 offset:39936
	global_load_lds_dwordx4 v[246:247], off
	v_lshl_add_u64 v[246:247], s[62:63], 0, v[174:175]
	s_mov_b32 m0, s68
	s_nop 0
	global_load_lds_dwordx4 v[246:247], off
	s_waitcnt vmcnt(8)
	s_waitcnt lgkmcnt(0)
	s_barrier
	s_setprio 1
	s_waitcnt lgkmcnt(0)
	v_mfma_f32_16x16x32_bf16 v[128:131], v[124:127], v[190:193], v[128:131]
	v_mfma_f32_16x16x32_bf16 v[120:123], v[136:139], v[190:193], v[120:123]
	v_mfma_f32_16x16x32_bf16 v[108:111], v[124:127], v[214:217], v[108:111]
	v_mfma_f32_16x16x32_bf16 v[104:107], v[136:139], v[214:217], v[104:107]
	v_mfma_f32_16x16x32_bf16 v[92:95], v[124:127], v[224:227], v[92:95]
	v_mfma_f32_16x16x32_bf16 v[88:91], v[136:139], v[224:227], v[88:91]
	v_mfma_f32_16x16x32_bf16 v[76:79], v[124:127], v[232:235], v[76:79]
	v_mfma_f32_16x16x32_bf16 v[72:75], v[136:139], v[232:235], v[72:75]
	v_mfma_f32_16x16x32_bf16 v[128:131], v[132:135], v[210:213], v[128:131]
	v_mfma_f32_16x16x32_bf16 v[120:123], v[140:143], v[210:213], v[120:123]
	v_mfma_f32_16x16x32_bf16 v[108:111], v[132:135], v[218:221], v[108:111]
	v_mfma_f32_16x16x32_bf16 v[104:107], v[140:143], v[218:221], v[104:107]
	v_mfma_f32_16x16x32_bf16 v[92:95], v[132:135], v[228:231], v[92:95]
	v_mfma_f32_16x16x32_bf16 v[88:91], v[140:143], v[228:231], v[88:91]
	v_mfma_f32_16x16x32_bf16 v[76:79], v[132:135], v[236:239], v[76:79]
	v_mfma_f32_16x16x32_bf16 v[72:75], v[140:143], v[236:239], v[72:75]
	s_setprio 0
	s_setprio 1
	v_mfma_f32_16x16x32_bf16 v[116:119], v[144:147], v[190:193], v[116:119]
	v_mfma_f32_16x16x32_bf16 v[112:115], v[182:185], v[190:193], v[112:115]
	v_mfma_f32_16x16x32_bf16 v[100:103], v[144:147], v[214:217], v[100:103]
	v_mfma_f32_16x16x32_bf16 v[96:99], v[182:185], v[214:217], v[96:99]
	v_mfma_f32_16x16x32_bf16 v[84:87], v[144:147], v[224:227], v[84:87]
	v_mfma_f32_16x16x32_bf16 v[80:83], v[182:185], v[224:227], v[80:83]
	v_mfma_f32_16x16x32_bf16 v[68:71], v[144:147], v[232:235], v[68:71]
	v_mfma_f32_16x16x32_bf16 v[64:67], v[182:185], v[232:235], v[64:67]
	v_mfma_f32_16x16x32_bf16 v[116:119], v[148:151], v[210:213], v[116:119]
	v_mfma_f32_16x16x32_bf16 v[112:115], v[186:189], v[210:213], v[112:115]
	v_mfma_f32_16x16x32_bf16 v[100:103], v[148:151], v[218:221], v[100:103]
	v_mfma_f32_16x16x32_bf16 v[96:99], v[186:189], v[218:221], v[96:99]
	v_mfma_f32_16x16x32_bf16 v[84:87], v[148:151], v[228:231], v[84:87]
	v_mfma_f32_16x16x32_bf16 v[80:83], v[186:189], v[228:231], v[80:83]
	v_mfma_f32_16x16x32_bf16 v[68:71], v[148:151], v[236:239], v[68:71]
	v_mfma_f32_16x16x32_bf16 v[64:67], v[186:189], v[236:239], v[64:67]
	s_setprio 0
	s_barrier
	s_add_i32 s62, s83, s8
	v_lshl_add_u64 v[198:199], v[198:199], 0, s[22:23]
	s_mov_b32 m0, s62
	ds_read_b128 v[190:193], v197 offset:49152
	ds_read_b128 v[210:213], v197 offset:50176
	ds_read_b128 v[214:217], v197 offset:51200
	ds_read_b128 v[218:221], v197 offset:52224
	ds_read_b128 v[224:227], v197 offset:53248
	ds_read_b128 v[228:231], v197 offset:54272
	ds_read_b128 v[232:235], v197 offset:55296
	ds_read_b128 v[236:239], v197 offset:56320
	global_load_lds_dwordx4 v[198:199], off
	s_add_i32 m0, s62, 0x2000
	s_add_u32 s44, s44, 0x20080
	v_lshl_add_u64 v[198:199], v[240:241], 0, s[22:23]
	s_addc_u32 s45, s45, 0
	s_add_i32 s62, s84, s8
	global_load_lds_dwordx4 v[198:199], off
	v_lshl_add_u64 v[198:199], s[44:45], 0, v[152:153]
	s_mov_b32 m0, s62
	s_nop 0
	global_load_lds_dwordx4 v[198:199], off
	v_lshl_add_u64 v[198:199], s[44:45], 0, v[172:173]
	s_add_i32 m0, s62, 0x2000
	s_nop 0
	global_load_lds_dwordx4 v[198:199], off
	v_lshl_add_u64 v[198:199], v[242:243], 0, s[22:23]
	s_mov_b32 m0, s69
	s_nop 0
	global_load_lds_dwordx4 v[198:199], off
	v_lshl_add_u64 v[198:199], v[244:245], 0, s[22:23]
	s_mov_b32 m0, s74
	s_nop 0
	global_load_lds_dwordx4 v[198:199], off
	s_waitcnt vmcnt(8)
	s_waitcnt lgkmcnt(0)
	s_barrier
	s_setprio 1
	s_waitcnt lgkmcnt(0)
	v_mfma_f32_16x16x32_bf16 v[60:63], v[124:127], v[190:193], v[60:63]
	v_mfma_f32_16x16x32_bf16 v[56:59], v[136:139], v[190:193], v[56:59]
	v_mfma_f32_16x16x32_bf16 v[48:51], v[124:127], v[214:217], v[48:51]
	v_mfma_f32_16x16x32_bf16 v[40:43], v[136:139], v[214:217], v[40:43]
	v_mfma_f32_16x16x32_bf16 v[32:35], v[124:127], v[224:227], v[32:35]
	v_mfma_f32_16x16x32_bf16 v[24:27], v[136:139], v[224:227], v[24:27]
	v_mfma_f32_16x16x32_bf16 v[16:19], v[124:127], v[232:235], v[16:19]
	v_mfma_f32_16x16x32_bf16 v[8:11], v[136:139], v[232:235], v[8:11]
	v_mfma_f32_16x16x32_bf16 v[60:63], v[132:135], v[210:213], v[60:63]
	v_mfma_f32_16x16x32_bf16 v[56:59], v[140:143], v[210:213], v[56:59]
	v_mfma_f32_16x16x32_bf16 v[48:51], v[132:135], v[218:221], v[48:51]
	v_mfma_f32_16x16x32_bf16 v[40:43], v[140:143], v[218:221], v[40:43]
	v_mfma_f32_16x16x32_bf16 v[32:35], v[132:135], v[228:231], v[32:35]
	v_mfma_f32_16x16x32_bf16 v[24:27], v[140:143], v[228:231], v[24:27]
	v_mfma_f32_16x16x32_bf16 v[16:19], v[132:135], v[236:239], v[16:19]
	v_mfma_f32_16x16x32_bf16 v[8:11], v[140:143], v[236:239], v[8:11]
	s_setprio 0
	s_setprio 1
	v_mfma_f32_16x16x32_bf16 v[52:55], v[144:147], v[190:193], v[52:55]
	v_mfma_f32_16x16x32_bf16 v[44:47], v[182:185], v[190:193], v[44:47]
	v_mfma_f32_16x16x32_bf16 v[36:39], v[144:147], v[214:217], v[36:39]
	v_mfma_f32_16x16x32_bf16 v[28:31], v[182:185], v[214:217], v[28:31]
	v_mfma_f32_16x16x32_bf16 v[20:23], v[144:147], v[224:227], v[20:23]
	v_mfma_f32_16x16x32_bf16 v[12:15], v[182:185], v[224:227], v[12:15]
	v_mfma_f32_16x16x32_bf16 v[4:7], v[144:147], v[232:235], v[4:7]
	v_mfma_f32_16x16x32_bf16 v[0:3], v[182:185], v[232:235], v[0:3]
	v_mfma_f32_16x16x32_bf16 v[52:55], v[148:151], v[210:213], v[52:55]
	v_mfma_f32_16x16x32_bf16 v[44:47], v[186:189], v[210:213], v[44:47]
	v_mfma_f32_16x16x32_bf16 v[36:39], v[148:151], v[218:221], v[36:39]
	v_mfma_f32_16x16x32_bf16 v[28:31], v[186:189], v[218:221], v[28:31]
	v_mfma_f32_16x16x32_bf16 v[20:23], v[148:151], v[228:231], v[20:23]
	v_mfma_f32_16x16x32_bf16 v[12:15], v[186:189], v[228:231], v[12:15]
	v_mfma_f32_16x16x32_bf16 v[4:7], v[148:151], v[236:239], v[4:7]
	v_mfma_f32_16x16x32_bf16 v[0:3], v[186:189], v[236:239], v[0:3]
	s_setprio 0
	s_barrier
	s_add_i32 s82, s82, 2
	s_add_u32 s80, s80, 0x100
	s_addc_u32 s81, s81, 0
	s_add_u32 s60, s60, 0x100
	s_addc_u32 s61, s61, 0
	s_cmp_gt_u32 s82, 5

.LBB0_718:
	s_add_i32 s83, 0, 0x10000
	s_add_i32 s86, 0, 0x14000
	v_add_u32_e32 v140, s83, v181
	v_add_u32_e32 v178, s86, v181
	ds_read_b128 v[128:131], v140
	ds_read_b128 v[132:135], v140 offset:1024
	ds_read_b128 v[136:139], v140 offset:2048
	ds_read_b128 v[140:143], v140 offset:3072
	ds_read_b128 v[174:177], v178
	ds_read_b128 v[184:187], v178 offset:1024
	ds_read_b128 v[188:191], v178 offset:2048
	ds_read_b128 v[192:195], v178 offset:3072
	ds_read_b128 v[196:199], v183
	ds_read_b128 v[210:213], v183 offset:1024
	ds_read_b128 v[214:217], v183 offset:2048
	ds_read_b128 v[218:221], v183 offset:3072
	ds_read_b128 v[224:227], v183 offset:4096
	ds_read_b128 v[228:231], v183 offset:5120
	ds_read_b128 v[232:235], v183 offset:6144
	ds_read_b128 v[236:239], v183 offset:7168
	s_add_i32 s75, s75, 1
	s_mul_i32 s19, s75, s33
	s_mul_hi_u32 s21, s75, s94
	s_add_i32 s21, s21, s19
	s_mul_i32 s19, s75, s94
	s_add_u32 s48, s19, s2
	s_addc_u32 s49, s21, s3
	v_cmp_gt_i64_e32 vcc, s[48:49], v[164:165]
	v_cmp_lt_i64_e64 s[46:47], s[48:49], v[162:163]
	s_cbranch_vccnz .LBB0_724
	s_ashr_i32 s18, s48, 31
	s_lshr_b32 s18, s18, 29
	s_add_i32 s20, s48, s18
	s_and_b32 s18, s20, -8
	s_sub_i32 s21, s48, s18
	s_cmp_gt_i32 s21, -1
	s_mov_b64 s[18:19], -1
	s_cbranch_scc0 .LBB0_721
	s_lshl_b32 s48, s21, 6
	s_mov_b64 s[18:19], 0

.LBB0_724:
	s_ashr_i32 s21, s20, 31
	s_lshl_b64 s[48:49], s[20:21], 18
	v_readlane_b32 s19, v254, 28
	s_add_u32 s48, s19, s48
	v_readlane_b32 s19, v254, 29
	s_addc_u32 s49, s19, s49
	s_and_b64 s[50:51], s[46:47], exec
	s_cselect_b32 s21, s49, s45
	s_cselect_b32 s78, s48, s44
	s_ashr_i32 s19, s18, 31
	s_lshl_b64 s[50:51], s[18:19], 18
	v_readlane_b32 s19, v254, 24
	s_add_u32 s50, s19, s50
	v_readlane_b32 s19, v254, 25
	s_addc_u32 s51, s19, s51
	s_and_b64 s[62:63], s[46:47], exec
	s_cselect_b32 s19, s51, s61
	s_cselect_b32 s79, s50, s60
	s_add_u32 s80, s60, 0x100
	s_addc_u32 s81, s61, 0
	s_add_u32 s60, s44, 0x20080
	s_addc_u32 s61, s45, 0
	s_mov_b32 s82, -2
	s_add_u32 s44, s60, 0xfffe0080
	s_addc_u32 s45, s61, -1
	s_cmp_eq_u32 s82, 4
	s_cselect_b32 s63, s21, s45
	s_cselect_b32 s62, s78, s44
	s_cselect_b32 s45, s19, s81
	s_cselect_b32 s44, s79, s80
	v_lshl_add_u64 v[178:179], s[60:61], 0, v[172:173]
	s_add_i32 m0, s59, 0xc000
	global_load_lds_dwordx4 v[178:179], off
	v_lshl_add_u64 v[178:179], s[60:61], 0, v[150:151]
	s_add_i32 m0, s59, 0xe000
	s_nop 0
	global_load_lds_dwordx4 v[178:179], off
	s_waitcnt vmcnt(8)
	s_waitcnt lgkmcnt(0)
	s_barrier
	s_setprio 1
	s_waitcnt lgkmcnt(0)
	v_mfma_f32_16x16x32_bf16 v[124:127], v[128:131], v[196:199], 0
	v_mfma_f32_16x16x32_bf16 v[120:123], v[136:139], v[196:199], 0
	v_mfma_f32_16x16x32_bf16 v[108:111], v[128:131], v[214:217], 0
	v_mfma_f32_16x16x32_bf16 v[104:107], v[136:139], v[214:217], 0
	v_mfma_f32_16x16x32_bf16 v[92:95], v[128:131], v[224:227], 0
	v_mfma_f32_16x16x32_bf16 v[88:91], v[136:139], v[224:227], 0
	v_mfma_f32_16x16x32_bf16 v[76:79], v[128:131], v[232:235], 0
	v_mfma_f32_16x16x32_bf16 v[72:75], v[136:139], v[232:235], 0
	v_mfma_f32_16x16x32_bf16 v[124:127], v[132:135], v[210:213], v[124:127]
	v_mfma_f32_16x16x32_bf16 v[120:123], v[140:143], v[210:213], v[120:123]
	v_mfma_f32_16x16x32_bf16 v[108:111], v[132:135], v[218:221], v[108:111]
	v_mfma_f32_16x16x32_bf16 v[104:107], v[140:143], v[218:221], v[104:107]
	v_mfma_f32_16x16x32_bf16 v[92:95], v[132:135], v[228:231], v[92:95]
	v_mfma_f32_16x16x32_bf16 v[88:91], v[140:143], v[228:231], v[88:91]
	v_mfma_f32_16x16x32_bf16 v[76:79], v[132:135], v[236:239], v[76:79]
	v_mfma_f32_16x16x32_bf16 v[72:75], v[140:143], v[236:239], v[72:75]
	s_setprio 0
	s_setprio 1
	v_mfma_f32_16x16x32_bf16 v[116:119], v[174:177], v[196:199], 0
	v_mfma_f32_16x16x32_bf16 v[112:115], v[188:191], v[196:199], 0
	v_mfma_f32_16x16x32_bf16 v[100:103], v[174:177], v[214:217], 0
	v_mfma_f32_16x16x32_bf16 v[96:99], v[188:191], v[214:217], 0
	v_mfma_f32_16x16x32_bf16 v[84:87], v[174:177], v[224:227], 0
	v_mfma_f32_16x16x32_bf16 v[80:83], v[188:191], v[224:227], 0
	v_mfma_f32_16x16x32_bf16 v[68:71], v[174:177], v[232:235], 0
	v_mfma_f32_16x16x32_bf16 v[64:67], v[188:191], v[232:235], 0
	v_mfma_f32_16x16x32_bf16 v[116:119], v[184:187], v[210:213], v[116:119]
	v_mfma_f32_16x16x32_bf16 v[112:115], v[192:195], v[210:213], v[112:115]
	v_mfma_f32_16x16x32_bf16 v[100:103], v[184:187], v[218:221], v[100:103]
	v_mfma_f32_16x16x32_bf16 v[96:99], v[192:195], v[218:221], v[96:99]
	v_mfma_f32_16x16x32_bf16 v[84:87], v[184:187], v[228:231], v[84:87]
	v_mfma_f32_16x16x32_bf16 v[80:83], v[192:195], v[228:231], v[80:83]
	v_mfma_f32_16x16x32_bf16 v[68:71], v[184:187], v[236:239], v[68:71]
	v_mfma_f32_16x16x32_bf16 v[64:67], v[192:195], v[236:239], v[64:67]
	s_setprio 0
	s_barrier
	s_add_i32 s83, s83, s8
	v_lshl_add_u64 v[178:179], s[44:45], 0, v[152:153]
	s_mov_b32 m0, s83
	ds_read_b128 v[196:199], v183 offset:16384
	ds_read_b128 v[210:213], v183 offset:17408
	ds_read_b128 v[214:217], v183 offset:18432
	ds_read_b128 v[218:221], v183 offset:19456
	ds_read_b128 v[224:227], v183 offset:20480
	ds_read_b128 v[228:231], v183 offset:21504
	ds_read_b128 v[232:235], v183 offset:22528
	ds_read_b128 v[236:239], v183 offset:23552
	global_load_lds_dwordx4 v[178:179], off
	s_add_i32 m0, s83, 0x2000
	s_add_u32 s84, s44, 0x20000
	v_lshl_add_u64 v[240:241], s[44:45], 0, v[144:145]
	s_addc_u32 s85, s45, 0
	s_add_i32 s83, s86, s8
	global_load_lds_dwordx4 v[240:241], off
	v_lshl_add_u64 v[242:243], s[84:85], 0, v[152:153]
	s_mov_b32 m0, s83
	v_lshl_add_u64 v[244:245], s[62:63], 0, v[146:147]
	global_load_lds_dwordx4 v[242:243], off
	v_lshl_add_u64 v[242:243], s[84:85], 0, v[144:145]
	s_add_i32 m0, s83, 0x2000
	s_nop 0
	global_load_lds_dwordx4 v[242:243], off
	v_lshl_add_u64 v[242:243], s[62:63], 0, v[148:149]
	s_mov_b32 m0, s59
	s_nop 0
	global_load_lds_dwordx4 v[242:243], off
	s_mov_b32 m0, s66
	s_nop 0
	global_load_lds_dwordx4 v[244:245], off
	s_waitcnt vmcnt(8)
	s_waitcnt lgkmcnt(0)
	s_barrier
	s_setprio 1
	s_waitcnt lgkmcnt(0)
	v_mfma_f32_16x16x32_bf16 v[60:63], v[128:131], v[196:199], 0
	v_mfma_f32_16x16x32_bf16 v[56:59], v[136:139], v[196:199], 0
	v_mfma_f32_16x16x32_bf16 v[44:47], v[128:131], v[214:217], 0
	v_mfma_f32_16x16x32_bf16 v[40:43], v[136:139], v[214:217], 0
	v_mfma_f32_16x16x32_bf16 v[28:31], v[128:131], v[224:227], 0
	v_mfma_f32_16x16x32_bf16 v[24:27], v[136:139], v[224:227], 0
	v_mfma_f32_16x16x32_bf16 v[12:15], v[128:131], v[232:235], 0
	v_mfma_f32_16x16x32_bf16 v[8:11], v[136:139], v[232:235], 0
	v_mfma_f32_16x16x32_bf16 v[60:63], v[132:135], v[210:213], v[60:63]
	v_mfma_f32_16x16x32_bf16 v[56:59], v[140:143], v[210:213], v[56:59]
	v_mfma_f32_16x16x32_bf16 v[44:47], v[132:135], v[218:221], v[44:47]
	v_mfma_f32_16x16x32_bf16 v[40:43], v[140:143], v[218:221], v[40:43]
	v_mfma_f32_16x16x32_bf16 v[28:31], v[132:135], v[228:231], v[28:31]
	v_mfma_f32_16x16x32_bf16 v[24:27], v[140:143], v[228:231], v[24:27]
	v_mfma_f32_16x16x32_bf16 v[12:15], v[132:135], v[236:239], v[12:15]
	v_mfma_f32_16x16x32_bf16 v[8:11], v[140:143], v[236:239], v[8:11]
	s_setprio 0
	s_setprio 1
	v_mfma_f32_16x16x32_bf16 v[52:55], v[174:177], v[196:199], 0
	v_mfma_f32_16x16x32_bf16 v[48:51], v[188:191], v[196:199], 0
	v_mfma_f32_16x16x32_bf16 v[36:39], v[174:177], v[214:217], 0
	v_mfma_f32_16x16x32_bf16 v[32:35], v[188:191], v[214:217], 0
	v_mfma_f32_16x16x32_bf16 v[20:23], v[174:177], v[224:227], 0
	v_mfma_f32_16x16x32_bf16 v[16:19], v[188:191], v[224:227], 0
	v_mfma_f32_16x16x32_bf16 v[4:7], v[174:177], v[232:235], 0
	v_mfma_f32_16x16x32_bf16 v[0:3], v[188:191], v[232:235], 0
	v_mfma_f32_16x16x32_bf16 v[52:55], v[184:187], v[210:213], v[52:55]
	v_mfma_f32_16x16x32_bf16 v[48:51], v[192:195], v[210:213], v[48:51]
	v_mfma_f32_16x16x32_bf16 v[36:39], v[184:187], v[218:221], v[36:39]
	v_mfma_f32_16x16x32_bf16 v[32:35], v[192:195], v[218:221], v[32:35]
	v_mfma_f32_16x16x32_bf16 v[20:23], v[184:187], v[228:231], v[20:23]
	v_mfma_f32_16x16x32_bf16 v[16:19], v[192:195], v[228:231], v[16:19]
	v_mfma_f32_16x16x32_bf16 v[4:7], v[184:187], v[236:239], v[4:7]
	v_mfma_f32_16x16x32_bf16 v[0:3], v[192:195], v[236:239], v[0:3]
	s_setprio 0
	s_barrier
	s_add_i32 s83, 0, 0x18000
	s_add_i32 s84, 0, 0x1c000
	v_add_u32_e32 v140, s83, v181
	v_add_u32_e32 v192, s84, v181
	ds_read_b128 v[128:131], v140
	ds_read_b128 v[132:135], v140 offset:1024
	ds_read_b128 v[136:139], v140 offset:2048
	ds_read_b128 v[140:143], v140 offset:3072
	ds_read_b128 v[174:177], v192
	ds_read_b128 v[184:187], v192 offset:1024
	ds_read_b128 v[188:191], v192 offset:2048
	ds_read_b128 v[192:195], v192 offset:3072
	s_add_u32 s62, s62, 0x20000
	s_addc_u32 s63, s63, 0
	s_mov_b32 m0, s67
	v_lshl_add_u64 v[246:247], s[62:63], 0, v[148:149]
	ds_read_b128 v[196:199], v183 offset:32768
	ds_read_b128 v[210:213], v183 offset:33792
	ds_read_b128 v[214:217], v183 offset:34816
	ds_read_b128 v[218:221], v183 offset:35840
	ds_read_b128 v[224:227], v183 offset:36864
	ds_read_b128 v[228:231], v183 offset:37888
	ds_read_b128 v[232:235], v183 offset:38912
	ds_read_b128 v[236:239], v183 offset:39936
	global_load_lds_dwordx4 v[246:247], off
	v_lshl_add_u64 v[246:247], s[62:63], 0, v[146:147]
	s_mov_b32 m0, s68
	s_nop 0
	global_load_lds_dwordx4 v[246:247], off
	s_waitcnt vmcnt(8)
	s_waitcnt lgkmcnt(0)
	s_barrier
	s_setprio 1
	s_waitcnt lgkmcnt(0)
	v_mfma_f32_16x16x32_bf16 v[124:127], v[128:131], v[196:199], v[124:127]
	v_mfma_f32_16x16x32_bf16 v[120:123], v[136:139], v[196:199], v[120:123]
	v_mfma_f32_16x16x32_bf16 v[108:111], v[128:131], v[214:217], v[108:111]
	v_mfma_f32_16x16x32_bf16 v[104:107], v[136:139], v[214:217], v[104:107]
	v_mfma_f32_16x16x32_bf16 v[92:95], v[128:131], v[224:227], v[92:95]
	v_mfma_f32_16x16x32_bf16 v[88:91], v[136:139], v[224:227], v[88:91]
	v_mfma_f32_16x16x32_bf16 v[76:79], v[128:131], v[232:235], v[76:79]
	v_mfma_f32_16x16x32_bf16 v[72:75], v[136:139], v[232:235], v[72:75]
	v_mfma_f32_16x16x32_bf16 v[124:127], v[132:135], v[210:213], v[124:127]
	v_mfma_f32_16x16x32_bf16 v[120:123], v[140:143], v[210:213], v[120:123]
	v_mfma_f32_16x16x32_bf16 v[108:111], v[132:135], v[218:221], v[108:111]
	v_mfma_f32_16x16x32_bf16 v[104:107], v[140:143], v[218:221], v[104:107]
	v_mfma_f32_16x16x32_bf16 v[92:95], v[132:135], v[228:231], v[92:95]
	v_mfma_f32_16x16x32_bf16 v[88:91], v[140:143], v[228:231], v[88:91]
	v_mfma_f32_16x16x32_bf16 v[76:79], v[132:135], v[236:239], v[76:79]
	v_mfma_f32_16x16x32_bf16 v[72:75], v[140:143], v[236:239], v[72:75]
	s_setprio 0
	s_setprio 1
	v_mfma_f32_16x16x32_bf16 v[116:119], v[174:177], v[196:199], v[116:119]
	v_mfma_f32_16x16x32_bf16 v[112:115], v[188:191], v[196:199], v[112:115]
	v_mfma_f32_16x16x32_bf16 v[100:103], v[174:177], v[214:217], v[100:103]
	v_mfma_f32_16x16x32_bf16 v[96:99], v[188:191], v[214:217], v[96:99]
	v_mfma_f32_16x16x32_bf16 v[84:87], v[174:177], v[224:227], v[84:87]
	v_mfma_f32_16x16x32_bf16 v[80:83], v[188:191], v[224:227], v[80:83]
	v_mfma_f32_16x16x32_bf16 v[68:71], v[174:177], v[232:235], v[68:71]
	v_mfma_f32_16x16x32_bf16 v[64:67], v[188:191], v[232:235], v[64:67]
	v_mfma_f32_16x16x32_bf16 v[116:119], v[184:187], v[210:213], v[116:119]
	v_mfma_f32_16x16x32_bf16 v[112:115], v[192:195], v[210:213], v[112:115]
	v_mfma_f32_16x16x32_bf16 v[100:103], v[184:187], v[218:221], v[100:103]
	v_mfma_f32_16x16x32_bf16 v[96:99], v[192:195], v[218:221], v[96:99]
	v_mfma_f32_16x16x32_bf16 v[84:87], v[184:187], v[228:231], v[84:87]
	v_mfma_f32_16x16x32_bf16 v[80:83], v[192:195], v[228:231], v[80:83]
	v_mfma_f32_16x16x32_bf16 v[68:71], v[184:187], v[236:239], v[68:71]
	v_mfma_f32_16x16x32_bf16 v[64:67], v[192:195], v[236:239], v[64:67]
	s_setprio 0
	s_barrier
	s_add_i32 s62, s83, s8
	v_lshl_add_u64 v[178:179], v[178:179], 0, s[22:23]
	s_mov_b32 m0, s62
	ds_read_b128 v[196:199], v183 offset:49152
	ds_read_b128 v[210:213], v183 offset:50176
	ds_read_b128 v[214:217], v183 offset:51200
	ds_read_b128 v[218:221], v183 offset:52224
	ds_read_b128 v[224:227], v183 offset:53248
	ds_read_b128 v[228:231], v183 offset:54272
	ds_read_b128 v[232:235], v183 offset:55296
	ds_read_b128 v[236:239], v183 offset:56320
	global_load_lds_dwordx4 v[178:179], off
	s_add_i32 m0, s62, 0x2000
	s_add_u32 s44, s44, 0x20080
	v_lshl_add_u64 v[178:179], v[240:241], 0, s[22:23]
	s_addc_u32 s45, s45, 0
	s_add_i32 s62, s84, s8
	global_load_lds_dwordx4 v[178:179], off
	v_lshl_add_u64 v[178:179], s[44:45], 0, v[152:153]
	s_mov_b32 m0, s62
	s_nop 0
	global_load_lds_dwordx4 v[178:179], off
	v_lshl_add_u64 v[178:179], s[44:45], 0, v[144:145]
	s_add_i32 m0, s62, 0x2000
	s_nop 0
	global_load_lds_dwordx4 v[178:179], off
	v_lshl_add_u64 v[178:179], v[242:243], 0, s[22:23]
	s_mov_b32 m0, s69
	s_nop 0
	global_load_lds_dwordx4 v[178:179], off
	v_lshl_add_u64 v[178:179], v[244:245], 0, s[22:23]
	s_mov_b32 m0, s74
	s_nop 0
	global_load_lds_dwordx4 v[178:179], off
	s_waitcnt vmcnt(8)
	s_waitcnt lgkmcnt(0)
	s_barrier
	s_setprio 1
	s_waitcnt lgkmcnt(0)
	v_mfma_f32_16x16x32_bf16 v[60:63], v[128:131], v[196:199], v[60:63]
	v_mfma_f32_16x16x32_bf16 v[56:59], v[136:139], v[196:199], v[56:59]
	v_mfma_f32_16x16x32_bf16 v[44:47], v[128:131], v[214:217], v[44:47]
	v_mfma_f32_16x16x32_bf16 v[40:43], v[136:139], v[214:217], v[40:43]
	v_mfma_f32_16x16x32_bf16 v[28:31], v[128:131], v[224:227], v[28:31]
	v_mfma_f32_16x16x32_bf16 v[24:27], v[136:139], v[224:227], v[24:27]
	v_mfma_f32_16x16x32_bf16 v[12:15], v[128:131], v[232:235], v[12:15]
	v_mfma_f32_16x16x32_bf16 v[8:11], v[136:139], v[232:235], v[8:11]
	v_mfma_f32_16x16x32_bf16 v[60:63], v[132:135], v[210:213], v[60:63]
	v_mfma_f32_16x16x32_bf16 v[56:59], v[140:143], v[210:213], v[56:59]
	v_mfma_f32_16x16x32_bf16 v[44:47], v[132:135], v[218:221], v[44:47]
	v_mfma_f32_16x16x32_bf16 v[40:43], v[140:143], v[218:221], v[40:43]
	v_mfma_f32_16x16x32_bf16 v[28:31], v[132:135], v[228:231], v[28:31]
	v_mfma_f32_16x16x32_bf16 v[24:27], v[140:143], v[228:231], v[24:27]
	v_mfma_f32_16x16x32_bf16 v[12:15], v[132:135], v[236:239], v[12:15]
	v_mfma_f32_16x16x32_bf16 v[8:11], v[140:143], v[236:239], v[8:11]
	s_setprio 0
	s_setprio 1
	v_mfma_f32_16x16x32_bf16 v[52:55], v[174:177], v[196:199], v[52:55]
	v_mfma_f32_16x16x32_bf16 v[48:51], v[188:191], v[196:199], v[48:51]
	v_mfma_f32_16x16x32_bf16 v[36:39], v[174:177], v[214:217], v[36:39]
	v_mfma_f32_16x16x32_bf16 v[32:35], v[188:191], v[214:217], v[32:35]
	v_mfma_f32_16x16x32_bf16 v[20:23], v[174:177], v[224:227], v[20:23]
	v_mfma_f32_16x16x32_bf16 v[16:19], v[188:191], v[224:227], v[16:19]
	v_mfma_f32_16x16x32_bf16 v[4:7], v[174:177], v[232:235], v[4:7]
	v_mfma_f32_16x16x32_bf16 v[0:3], v[188:191], v[232:235], v[0:3]
	v_mfma_f32_16x16x32_bf16 v[52:55], v[184:187], v[210:213], v[52:55]
	v_mfma_f32_16x16x32_bf16 v[48:51], v[192:195], v[210:213], v[48:51]
	v_mfma_f32_16x16x32_bf16 v[36:39], v[184:187], v[218:221], v[36:39]
	v_mfma_f32_16x16x32_bf16 v[32:35], v[192:195], v[218:221], v[32:35]
	v_mfma_f32_16x16x32_bf16 v[20:23], v[184:187], v[228:231], v[20:23]
	v_mfma_f32_16x16x32_bf16 v[16:19], v[192:195], v[228:231], v[16:19]
	v_mfma_f32_16x16x32_bf16 v[4:7], v[184:187], v[236:239], v[4:7]
	v_mfma_f32_16x16x32_bf16 v[0:3], v[192:195], v[236:239], v[0:3]
	s_setprio 0
	s_barrier
	s_add_i32 s82, s82, 2
	s_add_u32 s80, s80, 0x100
	s_addc_u32 s81, s81, 0
	s_add_u32 s60, s60, 0x100
	s_addc_u32 s61, s61, 0
	s_cmp_gt_u32 s82, 5

.LBB0_815:
	s_waitcnt lgkmcnt(0)
	s_add_i32 s86, 0, 0x10000
	s_add_i32 s89, 0, 0x14000
	v_add_u32_e32 v124, s86, v210
	v_add_u32_e32 v186, s89, v210
	ds_read_b128 v[112:115], v124
	ds_read_b128 v[116:119], v124 offset:1024
	ds_read_b128 v[120:123], v124 offset:2048
	ds_read_b128 v[124:127], v124 offset:3072
	ds_read_b128 v[132:135], v186
	ds_read_b128 v[140:143], v186 offset:1024
	ds_read_b128 v[182:185], v186 offset:2048
	ds_read_b128 v[186:189], v186 offset:3072
	ds_read_b128 v[190:193], v212
	ds_read_b128 v[194:197], v212 offset:1024
	ds_read_b128 v[214:217], v212 offset:2048
	ds_read_b128 v[218:221], v212 offset:3072
	ds_read_b128 v[224:227], v212 offset:4096
	ds_read_b128 v[228:231], v212 offset:5120
	ds_read_b128 v[232:235], v212 offset:6144
	ds_read_b128 v[236:239], v212 offset:7168
	s_add_i32 s79, s79, 1
	s_mul_i32 s19, s79, s33
	s_mul_hi_u32 s21, s79, s94
	s_add_i32 s21, s21, s19
	s_mul_i32 s19, s79, s94
	s_add_u32 s48, s19, s2
	s_addc_u32 s49, s21, s3
	v_cmp_gt_i64_e32 vcc, s[48:49], v[164:165]
	v_cmp_lt_i64_e64 s[46:47], s[48:49], v[162:163]
	s_cbranch_vccnz .LBB0_821
	s_ashr_i32 s18, s48, 31
	s_lshr_b32 s18, s18, 29
	s_add_i32 s20, s48, s18
	s_and_b32 s18, s20, -8
	s_sub_i32 s21, s48, s18
	s_cmp_gt_i32 s21, -1
	s_mov_b64 s[18:19], -1
	s_cbranch_scc0 .LBB0_818
	s_lshl_b32 s48, s21, 6
	s_mov_b64 s[18:19], 0

.LBB0_821:
	s_ashr_i32 s21, s20, 31
	s_lshl_b64 s[48:49], s[20:21], 19
	s_add_u32 s48, s70, s48
	s_addc_u32 s49, s71, s49
	s_and_b64 s[50:51], s[46:47], exec
	s_cselect_b32 s21, s49, s61
	s_cselect_b32 s81, s48, s60
	s_ashr_i32 s19, s18, 31
	s_lshl_b64 s[50:51], s[18:19], 19
	v_readlane_b32 s19, v254, 54
	s_add_u32 s50, s19, s50
	v_readlane_b32 s19, v254, 55
	s_addc_u32 s51, s19, s51
	s_and_b64 s[66:67], s[46:47], exec
	s_cselect_b32 s19, s51, s63
	s_cselect_b32 s82, s50, s62
	s_add_u32 s83, s62, 0x100
	s_addc_u32 s84, s63, 0
	s_add_u32 s60, s60, 0x40080
	s_addc_u32 s61, s61, 0
	s_mov_b32 s85, -2
	s_add_u32 s62, s60, 0xfffc0080
	s_addc_u32 s63, s61, -1
	s_cmp_eq_u32 s85, 12
	s_cselect_b32 s67, s21, s63
	s_cselect_b32 s66, s81, s62
	s_cselect_b32 s63, s19, s84
	s_cselect_b32 s62, s82, s83
	v_lshl_add_u64 v[198:199], s[60:61], 0, v[180:181]
	s_add_i32 m0, s68, 0xc000
	global_load_lds_dwordx4 v[198:199], off
	v_lshl_add_u64 v[198:199], s[60:61], 0, v[178:179]
	s_add_i32 m0, s68, 0xe000
	s_nop 0
	global_load_lds_dwordx4 v[198:199], off
	s_waitcnt vmcnt(8)
	s_waitcnt lgkmcnt(0)
	s_barrier
	s_setprio 1
	s_waitcnt lgkmcnt(0)
	v_mfma_f32_16x16x32_bf16 v[148:151], v[112:115], v[190:193], 0
	v_mfma_f32_16x16x32_bf16 v[144:147], v[120:123], v[190:193], 0
	v_mfma_f32_16x16x32_bf16 v[108:111], v[112:115], v[214:217], 0
	v_mfma_f32_16x16x32_bf16 v[104:107], v[120:123], v[214:217], 0
	v_mfma_f32_16x16x32_bf16 v[92:95], v[112:115], v[224:227], 0
	v_mfma_f32_16x16x32_bf16 v[88:91], v[120:123], v[224:227], 0
	v_mfma_f32_16x16x32_bf16 v[76:79], v[112:115], v[232:235], 0
	v_mfma_f32_16x16x32_bf16 v[72:75], v[120:123], v[232:235], 0
	v_mfma_f32_16x16x32_bf16 v[148:151], v[116:119], v[194:197], v[148:151]
	v_mfma_f32_16x16x32_bf16 v[144:147], v[124:127], v[194:197], v[144:147]
	v_mfma_f32_16x16x32_bf16 v[108:111], v[116:119], v[218:221], v[108:111]
	v_mfma_f32_16x16x32_bf16 v[104:107], v[124:127], v[218:221], v[104:107]
	v_mfma_f32_16x16x32_bf16 v[92:95], v[116:119], v[228:231], v[92:95]
	v_mfma_f32_16x16x32_bf16 v[88:91], v[124:127], v[228:231], v[88:91]
	v_mfma_f32_16x16x32_bf16 v[76:79], v[116:119], v[236:239], v[76:79]
	v_mfma_f32_16x16x32_bf16 v[72:75], v[124:127], v[236:239], v[72:75]
	s_setprio 0
	s_setprio 1
	v_mfma_f32_16x16x32_bf16 v[136:139], v[132:135], v[190:193], 0
	v_mfma_f32_16x16x32_bf16 v[128:131], v[182:185], v[190:193], 0
	v_mfma_f32_16x16x32_bf16 v[100:103], v[132:135], v[214:217], 0
	v_mfma_f32_16x16x32_bf16 v[96:99], v[182:185], v[214:217], 0
	v_mfma_f32_16x16x32_bf16 v[84:87], v[132:135], v[224:227], 0
	v_mfma_f32_16x16x32_bf16 v[80:83], v[182:185], v[224:227], 0
	v_mfma_f32_16x16x32_bf16 v[68:71], v[132:135], v[232:235], 0
	v_mfma_f32_16x16x32_bf16 v[64:67], v[182:185], v[232:235], 0
	v_mfma_f32_16x16x32_bf16 v[136:139], v[140:143], v[194:197], v[136:139]
	v_mfma_f32_16x16x32_bf16 v[128:131], v[186:189], v[194:197], v[128:131]
	v_mfma_f32_16x16x32_bf16 v[100:103], v[140:143], v[218:221], v[100:103]
	v_mfma_f32_16x16x32_bf16 v[96:99], v[186:189], v[218:221], v[96:99]
	v_mfma_f32_16x16x32_bf16 v[84:87], v[140:143], v[228:231], v[84:87]
	v_mfma_f32_16x16x32_bf16 v[80:83], v[186:189], v[228:231], v[80:83]
	v_mfma_f32_16x16x32_bf16 v[68:71], v[140:143], v[236:239], v[68:71]
	v_mfma_f32_16x16x32_bf16 v[64:67], v[186:189], v[236:239], v[64:67]
	s_setprio 0
	s_barrier
	s_add_i32 s86, s86, s59
	v_lshl_add_u64 v[198:199], s[62:63], 0, v[152:153]
	s_mov_b32 m0, s86
	ds_read_b128 v[190:193], v212 offset:16384
	ds_read_b128 v[194:197], v212 offset:17408
	ds_read_b128 v[214:217], v212 offset:18432
	ds_read_b128 v[218:221], v212 offset:19456
	ds_read_b128 v[224:227], v212 offset:20480
	ds_read_b128 v[228:231], v212 offset:21504
	ds_read_b128 v[232:235], v212 offset:22528
	ds_read_b128 v[236:239], v212 offset:23552
	global_load_lds_dwordx4 v[198:199], off
	s_add_i32 m0, s86, 0x2000
	s_add_u32 s86, s62, 0x40000
	v_lshl_add_u64 v[240:241], s[62:63], 0, v[172:173]
	s_addc_u32 s87, s63, 0
	s_add_i32 s89, s89, s59
	global_load_lds_dwordx4 v[240:241], off
	v_lshl_add_u64 v[242:243], s[86:87], 0, v[152:153]
	s_mov_b32 m0, s89
	v_lshl_add_u64 v[244:245], s[66:67], 0, v[174:175]
	global_load_lds_dwordx4 v[242:243], off
	v_lshl_add_u64 v[242:243], s[86:87], 0, v[172:173]
	s_add_i32 m0, s89, 0x2000
	s_nop 0
	global_load_lds_dwordx4 v[242:243], off
	v_lshl_add_u64 v[242:243], s[66:67], 0, v[176:177]
	s_mov_b32 m0, s68
	s_nop 0
	global_load_lds_dwordx4 v[242:243], off
	s_mov_b32 m0, s69
	s_nop 0
	global_load_lds_dwordx4 v[244:245], off
	s_waitcnt vmcnt(8)
	s_waitcnt lgkmcnt(0)
	s_barrier
	s_setprio 1
	s_waitcnt lgkmcnt(0)
	v_mfma_f32_16x16x32_bf16 v[60:63], v[112:115], v[190:193], 0
	v_mfma_f32_16x16x32_bf16 v[56:59], v[120:123], v[190:193], 0
	v_mfma_f32_16x16x32_bf16 v[44:47], v[112:115], v[214:217], 0
	v_mfma_f32_16x16x32_bf16 v[40:43], v[120:123], v[214:217], 0
	v_mfma_f32_16x16x32_bf16 v[28:31], v[112:115], v[224:227], 0
	v_mfma_f32_16x16x32_bf16 v[24:27], v[120:123], v[224:227], 0
	v_mfma_f32_16x16x32_bf16 v[12:15], v[112:115], v[232:235], 0
	v_mfma_f32_16x16x32_bf16 v[8:11], v[120:123], v[232:235], 0
	v_mfma_f32_16x16x32_bf16 v[60:63], v[116:119], v[194:197], v[60:63]
	v_mfma_f32_16x16x32_bf16 v[56:59], v[124:127], v[194:197], v[56:59]
	v_mfma_f32_16x16x32_bf16 v[44:47], v[116:119], v[218:221], v[44:47]
	v_mfma_f32_16x16x32_bf16 v[40:43], v[124:127], v[218:221], v[40:43]
	v_mfma_f32_16x16x32_bf16 v[28:31], v[116:119], v[228:231], v[28:31]
	v_mfma_f32_16x16x32_bf16 v[24:27], v[124:127], v[228:231], v[24:27]
	v_mfma_f32_16x16x32_bf16 v[12:15], v[116:119], v[236:239], v[12:15]
	v_mfma_f32_16x16x32_bf16 v[8:11], v[124:127], v[236:239], v[8:11]
	s_setprio 0
	s_setprio 1
	v_mfma_f32_16x16x32_bf16 v[52:55], v[132:135], v[190:193], 0
	v_mfma_f32_16x16x32_bf16 v[48:51], v[182:185], v[190:193], 0
	v_mfma_f32_16x16x32_bf16 v[36:39], v[132:135], v[214:217], 0
	v_mfma_f32_16x16x32_bf16 v[32:35], v[182:185], v[214:217], 0
	v_mfma_f32_16x16x32_bf16 v[20:23], v[132:135], v[224:227], 0
	v_mfma_f32_16x16x32_bf16 v[16:19], v[182:185], v[224:227], 0
	v_mfma_f32_16x16x32_bf16 v[4:7], v[132:135], v[232:235], 0
	v_mfma_f32_16x16x32_bf16 v[0:3], v[182:185], v[232:235], 0
	v_mfma_f32_16x16x32_bf16 v[52:55], v[140:143], v[194:197], v[52:55]
	v_mfma_f32_16x16x32_bf16 v[48:51], v[186:189], v[194:197], v[48:51]
	v_mfma_f32_16x16x32_bf16 v[36:39], v[140:143], v[218:221], v[36:39]
	v_mfma_f32_16x16x32_bf16 v[32:35], v[186:189], v[218:221], v[32:35]
	v_mfma_f32_16x16x32_bf16 v[20:23], v[140:143], v[228:231], v[20:23]
	v_mfma_f32_16x16x32_bf16 v[16:19], v[186:189], v[228:231], v[16:19]
	v_mfma_f32_16x16x32_bf16 v[4:7], v[140:143], v[236:239], v[4:7]
	v_mfma_f32_16x16x32_bf16 v[0:3], v[186:189], v[236:239], v[0:3]
	s_setprio 0
	s_barrier
	s_add_i32 s86, 0, 0x18000
	s_add_i32 s87, 0, 0x1c000
	v_add_u32_e32 v124, s86, v210
	v_add_u32_e32 v186, s87, v210
	ds_read_b128 v[112:115], v124
	ds_read_b128 v[116:119], v124 offset:1024
	ds_read_b128 v[120:123], v124 offset:2048
	ds_read_b128 v[124:127], v124 offset:3072
	ds_read_b128 v[132:135], v186
	ds_read_b128 v[140:143], v186 offset:1024
	ds_read_b128 v[182:185], v186 offset:2048
	ds_read_b128 v[186:189], v186 offset:3072
	s_add_u32 s66, s66, 0x40000
	s_addc_u32 s67, s67, 0
	s_mov_b32 m0, s74
	v_lshl_add_u64 v[246:247], s[66:67], 0, v[176:177]
	ds_read_b128 v[190:193], v212 offset:32768
	ds_read_b128 v[194:197], v212 offset:33792
	ds_read_b128 v[214:217], v212 offset:34816
	ds_read_b128 v[218:221], v212 offset:35840
	ds_read_b128 v[224:227], v212 offset:36864
	ds_read_b128 v[228:231], v212 offset:37888
	ds_read_b128 v[232:235], v212 offset:38912
	ds_read_b128 v[236:239], v212 offset:39936
	global_load_lds_dwordx4 v[246:247], off
	v_lshl_add_u64 v[246:247], s[66:67], 0, v[174:175]
	s_mov_b32 m0, s75
	s_nop 0
	global_load_lds_dwordx4 v[246:247], off
	s_waitcnt vmcnt(8)
	s_waitcnt lgkmcnt(0)
	s_barrier
	s_setprio 1
	s_waitcnt lgkmcnt(0)
	v_mfma_f32_16x16x32_bf16 v[148:151], v[112:115], v[190:193], v[148:151]
	v_mfma_f32_16x16x32_bf16 v[144:147], v[120:123], v[190:193], v[144:147]
	v_mfma_f32_16x16x32_bf16 v[108:111], v[112:115], v[214:217], v[108:111]
	v_mfma_f32_16x16x32_bf16 v[104:107], v[120:123], v[214:217], v[104:107]
	v_mfma_f32_16x16x32_bf16 v[92:95], v[112:115], v[224:227], v[92:95]
	v_mfma_f32_16x16x32_bf16 v[88:91], v[120:123], v[224:227], v[88:91]
	v_mfma_f32_16x16x32_bf16 v[76:79], v[112:115], v[232:235], v[76:79]
	v_mfma_f32_16x16x32_bf16 v[72:75], v[120:123], v[232:235], v[72:75]
	v_mfma_f32_16x16x32_bf16 v[148:151], v[116:119], v[194:197], v[148:151]
	v_mfma_f32_16x16x32_bf16 v[144:147], v[124:127], v[194:197], v[144:147]
	v_mfma_f32_16x16x32_bf16 v[108:111], v[116:119], v[218:221], v[108:111]
	v_mfma_f32_16x16x32_bf16 v[104:107], v[124:127], v[218:221], v[104:107]
	v_mfma_f32_16x16x32_bf16 v[92:95], v[116:119], v[228:231], v[92:95]
	v_mfma_f32_16x16x32_bf16 v[88:91], v[124:127], v[228:231], v[88:91]
	v_mfma_f32_16x16x32_bf16 v[76:79], v[116:119], v[236:239], v[76:79]
	v_mfma_f32_16x16x32_bf16 v[72:75], v[124:127], v[236:239], v[72:75]
	s_setprio 0
	s_setprio 1
	v_mfma_f32_16x16x32_bf16 v[136:139], v[132:135], v[190:193], v[136:139]
	v_mfma_f32_16x16x32_bf16 v[128:131], v[182:185], v[190:193], v[128:131]
	v_mfma_f32_16x16x32_bf16 v[100:103], v[132:135], v[214:217], v[100:103]
	v_mfma_f32_16x16x32_bf16 v[96:99], v[182:185], v[214:217], v[96:99]
	v_mfma_f32_16x16x32_bf16 v[84:87], v[132:135], v[224:227], v[84:87]
	v_mfma_f32_16x16x32_bf16 v[80:83], v[182:185], v[224:227], v[80:83]
	v_mfma_f32_16x16x32_bf16 v[68:71], v[132:135], v[232:235], v[68:71]
	v_mfma_f32_16x16x32_bf16 v[64:67], v[182:185], v[232:235], v[64:67]
	v_mfma_f32_16x16x32_bf16 v[136:139], v[140:143], v[194:197], v[136:139]
	v_mfma_f32_16x16x32_bf16 v[128:131], v[186:189], v[194:197], v[128:131]
	v_mfma_f32_16x16x32_bf16 v[100:103], v[140:143], v[218:221], v[100:103]
	v_mfma_f32_16x16x32_bf16 v[96:99], v[186:189], v[218:221], v[96:99]
	v_mfma_f32_16x16x32_bf16 v[84:87], v[140:143], v[228:231], v[84:87]
	v_mfma_f32_16x16x32_bf16 v[80:83], v[186:189], v[228:231], v[80:83]
	v_mfma_f32_16x16x32_bf16 v[68:71], v[140:143], v[236:239], v[68:71]
	v_mfma_f32_16x16x32_bf16 v[64:67], v[186:189], v[236:239], v[64:67]
	s_setprio 0
	s_barrier
	s_add_i32 s66, s86, s59
	v_lshl_add_u64 v[198:199], v[198:199], 0, s[22:23]
	s_mov_b32 m0, s66
	ds_read_b128 v[190:193], v212 offset:49152
	ds_read_b128 v[194:197], v212 offset:50176
	ds_read_b128 v[214:217], v212 offset:51200
	ds_read_b128 v[218:221], v212 offset:52224
	ds_read_b128 v[224:227], v212 offset:53248
	ds_read_b128 v[228:231], v212 offset:54272
	ds_read_b128 v[232:235], v212 offset:55296
	ds_read_b128 v[236:239], v212 offset:56320
	global_load_lds_dwordx4 v[198:199], off
	s_add_i32 m0, s66, 0x2000
	s_add_u32 s62, s62, 0x40080
	v_lshl_add_u64 v[198:199], v[240:241], 0, s[22:23]
	s_addc_u32 s63, s63, 0
	s_add_i32 s66, s87, s59
	global_load_lds_dwordx4 v[198:199], off
	v_lshl_add_u64 v[198:199], s[62:63], 0, v[152:153]
	s_mov_b32 m0, s66
	s_nop 0
	global_load_lds_dwordx4 v[198:199], off
	v_lshl_add_u64 v[198:199], s[62:63], 0, v[172:173]
	s_add_i32 m0, s66, 0x2000
	s_nop 0
	global_load_lds_dwordx4 v[198:199], off
	v_lshl_add_u64 v[198:199], v[242:243], 0, s[22:23]
	s_mov_b32 m0, s77
	s_nop 0
	global_load_lds_dwordx4 v[198:199], off
	v_lshl_add_u64 v[198:199], v[244:245], 0, s[22:23]
	s_mov_b32 m0, s78
	s_nop 0
	global_load_lds_dwordx4 v[198:199], off
	s_waitcnt vmcnt(8)
	s_waitcnt lgkmcnt(0)
	s_barrier
	s_setprio 1
	s_waitcnt lgkmcnt(0)
	v_mfma_f32_16x16x32_bf16 v[60:63], v[112:115], v[190:193], v[60:63]
	v_mfma_f32_16x16x32_bf16 v[56:59], v[120:123], v[190:193], v[56:59]
	v_mfma_f32_16x16x32_bf16 v[44:47], v[112:115], v[214:217], v[44:47]
	v_mfma_f32_16x16x32_bf16 v[40:43], v[120:123], v[214:217], v[40:43]
	v_mfma_f32_16x16x32_bf16 v[28:31], v[112:115], v[224:227], v[28:31]
	v_mfma_f32_16x16x32_bf16 v[24:27], v[120:123], v[224:227], v[24:27]
	v_mfma_f32_16x16x32_bf16 v[12:15], v[112:115], v[232:235], v[12:15]
	v_mfma_f32_16x16x32_bf16 v[8:11], v[120:123], v[232:235], v[8:11]
	v_mfma_f32_16x16x32_bf16 v[60:63], v[116:119], v[194:197], v[60:63]
	v_mfma_f32_16x16x32_bf16 v[56:59], v[124:127], v[194:197], v[56:59]
	v_mfma_f32_16x16x32_bf16 v[44:47], v[116:119], v[218:221], v[44:47]
	v_mfma_f32_16x16x32_bf16 v[40:43], v[124:127], v[218:221], v[40:43]
	v_mfma_f32_16x16x32_bf16 v[28:31], v[116:119], v[228:231], v[28:31]
	v_mfma_f32_16x16x32_bf16 v[24:27], v[124:127], v[228:231], v[24:27]
	v_mfma_f32_16x16x32_bf16 v[12:15], v[116:119], v[236:239], v[12:15]
	v_mfma_f32_16x16x32_bf16 v[8:11], v[124:127], v[236:239], v[8:11]
	s_setprio 0
	s_setprio 1
	v_mfma_f32_16x16x32_bf16 v[52:55], v[132:135], v[190:193], v[52:55]
	v_mfma_f32_16x16x32_bf16 v[48:51], v[182:185], v[190:193], v[48:51]
	v_mfma_f32_16x16x32_bf16 v[36:39], v[132:135], v[214:217], v[36:39]
	v_mfma_f32_16x16x32_bf16 v[32:35], v[182:185], v[214:217], v[32:35]
	v_mfma_f32_16x16x32_bf16 v[20:23], v[132:135], v[224:227], v[20:23]
	v_mfma_f32_16x16x32_bf16 v[16:19], v[182:185], v[224:227], v[16:19]
	v_mfma_f32_16x16x32_bf16 v[4:7], v[132:135], v[232:235], v[4:7]
	v_mfma_f32_16x16x32_bf16 v[0:3], v[182:185], v[232:235], v[0:3]
	v_mfma_f32_16x16x32_bf16 v[52:55], v[140:143], v[194:197], v[52:55]
	v_mfma_f32_16x16x32_bf16 v[48:51], v[186:189], v[194:197], v[48:51]
	v_mfma_f32_16x16x32_bf16 v[36:39], v[140:143], v[218:221], v[36:39]
	v_mfma_f32_16x16x32_bf16 v[32:35], v[186:189], v[218:221], v[32:35]
	v_mfma_f32_16x16x32_bf16 v[20:23], v[140:143], v[228:231], v[20:23]
	v_mfma_f32_16x16x32_bf16 v[16:19], v[186:189], v[228:231], v[16:19]
	v_mfma_f32_16x16x32_bf16 v[4:7], v[140:143], v[236:239], v[4:7]
	v_mfma_f32_16x16x32_bf16 v[0:3], v[186:189], v[236:239], v[0:3]
	s_setprio 0
	s_barrier
	s_add_i32 s85, s85, 2
	s_add_u32 s83, s83, 0x100
	s_addc_u32 s84, s84, 0
	s_add_u32 s60, s60, 0x100
	s_addc_u32 s61, s61, 0
	s_cmp_gt_u32 s85, 13
